# K-loop bodies: s_nop 0 inserted so every 8-byte instruction (MFMA, ds_read_b128, LDS-DMA) in the five GEMM loops starts at an address = 0 mod 8
# speedup vs baseline: 1.0055x; 1.0055x over previous
.LBB0_178:
	s_waitcnt lgkmcnt(0)
	ds_read_b128 v[160:163], v240
	ds_read_b128 v[164:167], v240 offset:1024
	ds_read_b128 v[178:181], v240 offset:2048
	ds_read_b128 v[182:185], v240 offset:3072
	s_add_u32 s44, s0, s30
	s_nop 0
	ds_read_b128 v[186:189], v240 offset:16384
	ds_read_b128 v[190:193], v240 offset:17408
	ds_read_b128 v[194:197], v240 offset:18432
	ds_read_b128 v[198:201], v240 offset:19456
	s_addc_u32 s45, s1, s31
	s_nop 0
	s_add_u32 s44, s44, 0x100
	s_addc_u32 s45, s45, 0
	s_add_u32 s72, s65, s30
	s_addc_u32 s73, s66, s31
	s_cmpk_eq_i32 s30, 0x700
	s_cselect_b32 s47, s29, s45
	s_cselect_b32 s46, s62, s44
	s_cselect_b32 s45, s63, s73
	s_cselect_b32 s44, s64, s72
	s_add_u32 s90, s0, s30
	s_addc_u32 s91, s1, s31
	s_add_i32 m0, s43, 0xc000
	ds_read_b128 v[202:205], v176
	ds_read_b128 v[206:209], v176 offset:1024
	ds_read_b128 v[210:213], v176 offset:2048
	ds_read_b128 v[214:217], v176 offset:3072
	ds_read_b128 v[218:221], v176 offset:4096
	ds_read_b128 v[222:225], v176 offset:5120
	ds_read_b128 v[226:229], v176 offset:6144
	ds_read_b128 v[230:233], v176 offset:7168
	global_load_lds_dwordx4 v148, s[90:91]
	s_add_i32 m0, s43, 0xe000
	s_nop 0
	s_nop 0
	global_load_lds_dwordx4 v150, s[90:91]
	s_waitcnt vmcnt(8)
	s_waitcnt lgkmcnt(0)
	s_barrier
	s_setprio 1
	v_mfma_f32_16x16x32_bf16 v[126:129], v[160:163], v[202:205], v[126:129]
	v_mfma_f32_16x16x32_bf16 v[126:129], v[164:167], v[206:209], v[126:129]
	v_mfma_f32_16x16x32_bf16 v[122:125], v[178:181], v[202:205], v[122:125]
	v_mfma_f32_16x16x32_bf16 v[122:125], v[182:185], v[206:209], v[122:125]
	v_mfma_f32_16x16x32_bf16 v[106:109], v[178:181], v[210:213], v[106:109]
	v_mfma_f32_16x16x32_bf16 v[106:109], v[182:185], v[214:217], v[106:109]
	v_mfma_f32_16x16x32_bf16 v[110:113], v[160:163], v[210:213], v[110:113]
	v_mfma_f32_16x16x32_bf16 v[110:113], v[164:167], v[214:217], v[110:113]
	v_mfma_f32_16x16x32_bf16 v[94:97], v[160:163], v[218:221], v[94:97]
	v_mfma_f32_16x16x32_bf16 v[94:97], v[164:167], v[222:225], v[94:97]
	v_mfma_f32_16x16x32_bf16 v[90:93], v[178:181], v[218:221], v[90:93]
	v_mfma_f32_16x16x32_bf16 v[90:93], v[182:185], v[222:225], v[90:93]
	v_mfma_f32_16x16x32_bf16 v[74:77], v[178:181], v[226:229], v[74:77]
	v_mfma_f32_16x16x32_bf16 v[74:77], v[182:185], v[230:233], v[74:77]
	v_mfma_f32_16x16x32_bf16 v[78:81], v[160:163], v[226:229], v[78:81]
	v_mfma_f32_16x16x32_bf16 v[78:81], v[164:167], v[230:233], v[78:81]
	v_mfma_f32_16x16x32_bf16 v[118:121], v[186:189], v[202:205], v[118:121]
	v_mfma_f32_16x16x32_bf16 v[118:121], v[190:193], v[206:209], v[118:121]
	v_mfma_f32_16x16x32_bf16 v[114:117], v[194:197], v[202:205], v[114:117]
	v_mfma_f32_16x16x32_bf16 v[114:117], v[198:201], v[206:209], v[114:117]
	v_mfma_f32_16x16x32_bf16 v[98:101], v[194:197], v[210:213], v[98:101]
	v_mfma_f32_16x16x32_bf16 v[98:101], v[198:201], v[214:217], v[98:101]
	v_mfma_f32_16x16x32_bf16 v[102:105], v[186:189], v[210:213], v[102:105]
	v_mfma_f32_16x16x32_bf16 v[102:105], v[190:193], v[214:217], v[102:105]
	v_mfma_f32_16x16x32_bf16 v[86:89], v[186:189], v[218:221], v[86:89]
	v_mfma_f32_16x16x32_bf16 v[86:89], v[190:193], v[222:225], v[86:89]
	v_mfma_f32_16x16x32_bf16 v[82:85], v[194:197], v[218:221], v[82:85]
	v_mfma_f32_16x16x32_bf16 v[82:85], v[198:201], v[222:225], v[82:85]
	s_setprio 2
	s_barrier
	v_mfma_f32_16x16x32_bf16 v[66:69], v[194:197], v[226:229], v[66:69]
	v_mfma_f32_16x16x32_bf16 v[66:69], v[198:201], v[230:233], v[66:69]
	v_mfma_f32_16x16x32_bf16 v[70:73], v[186:189], v[226:229], v[70:73]
	v_mfma_f32_16x16x32_bf16 v[70:73], v[190:193], v[230:233], v[70:73]
	s_setprio 0
	s_nop 0
	s_add_i32 s72, s60, s33
	s_mov_b32 m0, s72
	ds_read_b128 v[202:205], v176 offset:16384
	ds_read_b128 v[206:209], v176 offset:17408
	ds_read_b128 v[210:213], v176 offset:18432
	ds_read_b128 v[214:217], v176 offset:19456
	ds_read_b128 v[218:221], v176 offset:20480
	ds_read_b128 v[222:225], v176 offset:21504
	ds_read_b128 v[226:229], v176 offset:22528
	ds_read_b128 v[230:233], v176 offset:23552
	global_load_lds_dwordx4 v140, s[44:45]
	s_add_i32 m0, s72, 0x2000
	s_add_u32 s72, s44, 0x40000
	s_addc_u32 s73, s45, 0
	s_add_i32 s74, s61, s33
	global_load_lds_dwordx4 v144, s[44:45]
	s_mov_b32 m0, s74
	s_nop 0
	s_add_u32 s94, s46, 0x80
	s_addc_u32 s95, s47, 0
	s_nop 0
	global_load_lds_dwordx4 v140, s[72:73]
	s_add_i32 m0, s74, 0x2000
	s_nop 0
	s_nop 0
	global_load_lds_dwordx4 v144, s[72:73]
	s_mov_b32 m0, s43
	s_nop 0
	global_load_lds_dwordx4 v138, s[46:47]
	s_mov_b32 m0, s54
	s_nop 0
	global_load_lds_dwordx4 v142, s[46:47]
	s_waitcnt vmcnt(8)
	s_waitcnt lgkmcnt(0)
	s_barrier
	s_setprio 1
	v_mfma_f32_16x16x32_bf16 v[62:65], v[160:163], v[202:205], v[62:65]
	v_mfma_f32_16x16x32_bf16 v[62:65], v[164:167], v[206:209], v[62:65]
	v_mfma_f32_16x16x32_bf16 v[58:61], v[178:181], v[202:205], v[58:61]
	v_mfma_f32_16x16x32_bf16 v[58:61], v[182:185], v[206:209], v[58:61]
	v_mfma_f32_16x16x32_bf16 v[42:45], v[178:181], v[210:213], v[42:45]
	v_mfma_f32_16x16x32_bf16 v[42:45], v[182:185], v[214:217], v[42:45]
	v_mfma_f32_16x16x32_bf16 v[46:49], v[160:163], v[210:213], v[46:49]
	v_mfma_f32_16x16x32_bf16 v[46:49], v[164:167], v[214:217], v[46:49]
	v_mfma_f32_16x16x32_bf16 v[30:33], v[160:163], v[218:221], v[30:33]
	v_mfma_f32_16x16x32_bf16 v[30:33], v[164:167], v[222:225], v[30:33]
	v_mfma_f32_16x16x32_bf16 v[26:29], v[178:181], v[218:221], v[26:29]
	v_mfma_f32_16x16x32_bf16 v[26:29], v[182:185], v[222:225], v[26:29]
	v_mfma_f32_16x16x32_bf16 v[10:13], v[178:181], v[226:229], v[10:13]
	v_mfma_f32_16x16x32_bf16 v[10:13], v[182:185], v[230:233], v[10:13]
	v_mfma_f32_16x16x32_bf16 v[14:17], v[160:163], v[226:229], v[14:17]
	v_mfma_f32_16x16x32_bf16 v[14:17], v[164:167], v[230:233], v[14:17]
	v_mfma_f32_16x16x32_bf16 v[54:57], v[186:189], v[202:205], v[54:57]
	v_mfma_f32_16x16x32_bf16 v[54:57], v[190:193], v[206:209], v[54:57]
	v_mfma_f32_16x16x32_bf16 v[50:53], v[194:197], v[202:205], v[50:53]
	v_mfma_f32_16x16x32_bf16 v[50:53], v[198:201], v[206:209], v[50:53]
	v_mfma_f32_16x16x32_bf16 v[34:37], v[194:197], v[210:213], v[34:37]
	v_mfma_f32_16x16x32_bf16 v[34:37], v[198:201], v[214:217], v[34:37]
	v_mfma_f32_16x16x32_bf16 v[38:41], v[186:189], v[210:213], v[38:41]
	v_mfma_f32_16x16x32_bf16 v[38:41], v[190:193], v[214:217], v[38:41]
	v_mfma_f32_16x16x32_bf16 v[22:25], v[186:189], v[218:221], v[22:25]
	v_mfma_f32_16x16x32_bf16 v[22:25], v[190:193], v[222:225], v[22:25]
	v_mfma_f32_16x16x32_bf16 v[18:21], v[194:197], v[218:221], v[18:21]
	v_mfma_f32_16x16x32_bf16 v[18:21], v[198:201], v[222:225], v[18:21]
	s_setprio 2
	s_barrier
	v_mfma_f32_16x16x32_bf16 v[2:5], v[194:197], v[226:229], v[2:5]
	v_mfma_f32_16x16x32_bf16 v[2:5], v[198:201], v[230:233], v[2:5]
	v_mfma_f32_16x16x32_bf16 v[6:9], v[186:189], v[226:229], v[6:9]
	v_mfma_f32_16x16x32_bf16 v[6:9], v[190:193], v[230:233], v[6:9]
	s_setprio 0
	s_nop 0
	s_add_i32 s72, 0, 0x18000
	s_add_i32 s73, 0, 0x1c000
	ds_read_b128 v[160:163], v240 offset:32768
	ds_read_b128 v[164:167], v240 offset:33792
	ds_read_b128 v[178:181], v240 offset:34816
	ds_read_b128 v[182:185], v240 offset:35840
	ds_read_b128 v[186:189], v240 offset:49152
	ds_read_b128 v[190:193], v240 offset:50176
	ds_read_b128 v[194:197], v240 offset:51200
	ds_read_b128 v[198:201], v240 offset:52224
	s_add_u32 s46, s46, 0x40000
	s_addc_u32 s47, s47, 0
	s_mov_b32 m0, s55
	ds_read_b128 v[202:205], v176 offset:32768
	ds_read_b128 v[206:209], v176 offset:33792
	ds_read_b128 v[210:213], v176 offset:34816
	ds_read_b128 v[214:217], v176 offset:35840
	ds_read_b128 v[218:221], v176 offset:36864
	ds_read_b128 v[222:225], v176 offset:37888
	ds_read_b128 v[226:229], v176 offset:38912
	ds_read_b128 v[230:233], v176 offset:39936
	global_load_lds_dwordx4 v138, s[46:47]
	s_mov_b32 m0, s56
	s_nop 0
	global_load_lds_dwordx4 v142, s[46:47]
	s_waitcnt vmcnt(8)
	s_waitcnt lgkmcnt(0)
	s_barrier
	s_setprio 1
	v_mfma_f32_16x16x32_bf16 v[126:129], v[160:163], v[202:205], v[126:129]
	v_mfma_f32_16x16x32_bf16 v[126:129], v[164:167], v[206:209], v[126:129]
	v_mfma_f32_16x16x32_bf16 v[122:125], v[178:181], v[202:205], v[122:125]
	v_mfma_f32_16x16x32_bf16 v[122:125], v[182:185], v[206:209], v[122:125]
	v_mfma_f32_16x16x32_bf16 v[106:109], v[178:181], v[210:213], v[106:109]
	v_mfma_f32_16x16x32_bf16 v[106:109], v[182:185], v[214:217], v[106:109]
	v_mfma_f32_16x16x32_bf16 v[110:113], v[160:163], v[210:213], v[110:113]
	v_mfma_f32_16x16x32_bf16 v[110:113], v[164:167], v[214:217], v[110:113]
	v_mfma_f32_16x16x32_bf16 v[94:97], v[160:163], v[218:221], v[94:97]
	v_mfma_f32_16x16x32_bf16 v[94:97], v[164:167], v[222:225], v[94:97]
	v_mfma_f32_16x16x32_bf16 v[90:93], v[178:181], v[218:221], v[90:93]
	v_mfma_f32_16x16x32_bf16 v[90:93], v[182:185], v[222:225], v[90:93]
	v_mfma_f32_16x16x32_bf16 v[74:77], v[178:181], v[226:229], v[74:77]
	v_mfma_f32_16x16x32_bf16 v[74:77], v[182:185], v[230:233], v[74:77]
	v_mfma_f32_16x16x32_bf16 v[78:81], v[160:163], v[226:229], v[78:81]
	v_mfma_f32_16x16x32_bf16 v[78:81], v[164:167], v[230:233], v[78:81]
	v_mfma_f32_16x16x32_bf16 v[118:121], v[186:189], v[202:205], v[118:121]
	v_mfma_f32_16x16x32_bf16 v[118:121], v[190:193], v[206:209], v[118:121]
	v_mfma_f32_16x16x32_bf16 v[114:117], v[194:197], v[202:205], v[114:117]
	v_mfma_f32_16x16x32_bf16 v[114:117], v[198:201], v[206:209], v[114:117]
	v_mfma_f32_16x16x32_bf16 v[98:101], v[194:197], v[210:213], v[98:101]
	v_mfma_f32_16x16x32_bf16 v[98:101], v[198:201], v[214:217], v[98:101]
	v_mfma_f32_16x16x32_bf16 v[102:105], v[186:189], v[210:213], v[102:105]
	v_mfma_f32_16x16x32_bf16 v[102:105], v[190:193], v[214:217], v[102:105]
	v_mfma_f32_16x16x32_bf16 v[86:89], v[186:189], v[218:221], v[86:89]
	v_mfma_f32_16x16x32_bf16 v[86:89], v[190:193], v[222:225], v[86:89]
	v_mfma_f32_16x16x32_bf16 v[82:85], v[194:197], v[218:221], v[82:85]
	v_mfma_f32_16x16x32_bf16 v[82:85], v[198:201], v[222:225], v[82:85]
	s_setprio 2
	s_barrier
	v_mfma_f32_16x16x32_bf16 v[66:69], v[194:197], v[226:229], v[66:69]
	v_mfma_f32_16x16x32_bf16 v[66:69], v[198:201], v[230:233], v[66:69]
	v_mfma_f32_16x16x32_bf16 v[70:73], v[186:189], v[226:229], v[70:73]
	v_mfma_f32_16x16x32_bf16 v[70:73], v[190:193], v[230:233], v[70:73]
	s_setprio 0
	s_nop 0
	s_add_i32 s46, s72, s33
	s_nop 0
	s_add_u32 s96, s44, 0x80
	s_addc_u32 s97, s45, 0
	s_mov_b32 m0, s46
	ds_read_b128 v[202:205], v176 offset:49152
	ds_read_b128 v[206:209], v176 offset:50176
	ds_read_b128 v[210:213], v176 offset:51200
	ds_read_b128 v[214:217], v176 offset:52224
	ds_read_b128 v[218:221], v176 offset:53248
	ds_read_b128 v[222:225], v176 offset:54272
	ds_read_b128 v[226:229], v176 offset:55296
	ds_read_b128 v[230:233], v176 offset:56320
	global_load_lds_dwordx4 v140, s[96:97]
	s_add_i32 m0, s46, 0x2000
	s_add_u32 s44, s44, 0x40080
	s_addc_u32 s45, s45, 0
	s_add_i32 s46, s73, s33
	global_load_lds_dwordx4 v144, s[96:97]
	s_mov_b32 m0, s46
	s_nop 0
	global_load_lds_dwordx4 v140, s[44:45]
	s_add_i32 m0, s46, 0x2000
	s_nop 0
	s_nop 0
	global_load_lds_dwordx4 v144, s[44:45]
	s_mov_b32 m0, s57
	s_nop 0
	global_load_lds_dwordx4 v138, s[94:95]
	s_mov_b32 m0, s58
	s_nop 0
	global_load_lds_dwordx4 v142, s[94:95]
	s_waitcnt vmcnt(8)
	s_waitcnt lgkmcnt(0)
	s_barrier
	s_setprio 1
	v_mfma_f32_16x16x32_bf16 v[62:65], v[160:163], v[202:205], v[62:65]
	v_mfma_f32_16x16x32_bf16 v[62:65], v[164:167], v[206:209], v[62:65]
	v_mfma_f32_16x16x32_bf16 v[58:61], v[178:181], v[202:205], v[58:61]
	v_mfma_f32_16x16x32_bf16 v[58:61], v[182:185], v[206:209], v[58:61]
	v_mfma_f32_16x16x32_bf16 v[42:45], v[178:181], v[210:213], v[42:45]
	v_mfma_f32_16x16x32_bf16 v[42:45], v[182:185], v[214:217], v[42:45]
	v_mfma_f32_16x16x32_bf16 v[46:49], v[160:163], v[210:213], v[46:49]
	v_mfma_f32_16x16x32_bf16 v[46:49], v[164:167], v[214:217], v[46:49]
	v_mfma_f32_16x16x32_bf16 v[30:33], v[160:163], v[218:221], v[30:33]
	v_mfma_f32_16x16x32_bf16 v[30:33], v[164:167], v[222:225], v[30:33]
	v_mfma_f32_16x16x32_bf16 v[26:29], v[178:181], v[218:221], v[26:29]
	v_mfma_f32_16x16x32_bf16 v[26:29], v[182:185], v[222:225], v[26:29]
	v_mfma_f32_16x16x32_bf16 v[10:13], v[178:181], v[226:229], v[10:13]
	v_mfma_f32_16x16x32_bf16 v[10:13], v[182:185], v[230:233], v[10:13]
	v_mfma_f32_16x16x32_bf16 v[14:17], v[160:163], v[226:229], v[14:17]
	v_mfma_f32_16x16x32_bf16 v[14:17], v[164:167], v[230:233], v[14:17]
	v_mfma_f32_16x16x32_bf16 v[54:57], v[186:189], v[202:205], v[54:57]
	v_mfma_f32_16x16x32_bf16 v[54:57], v[190:193], v[206:209], v[54:57]
	v_mfma_f32_16x16x32_bf16 v[50:53], v[194:197], v[202:205], v[50:53]
	v_mfma_f32_16x16x32_bf16 v[50:53], v[198:201], v[206:209], v[50:53]
	v_mfma_f32_16x16x32_bf16 v[34:37], v[194:197], v[210:213], v[34:37]
	v_mfma_f32_16x16x32_bf16 v[34:37], v[198:201], v[214:217], v[34:37]
	v_mfma_f32_16x16x32_bf16 v[38:41], v[186:189], v[210:213], v[38:41]
	v_mfma_f32_16x16x32_bf16 v[38:41], v[190:193], v[214:217], v[38:41]
	v_mfma_f32_16x16x32_bf16 v[22:25], v[186:189], v[218:221], v[22:25]
	v_mfma_f32_16x16x32_bf16 v[22:25], v[190:193], v[222:225], v[22:25]
	v_mfma_f32_16x16x32_bf16 v[18:21], v[194:197], v[218:221], v[18:21]
	v_mfma_f32_16x16x32_bf16 v[18:21], v[198:201], v[222:225], v[18:21]
	s_setprio 2
	s_barrier
	v_mfma_f32_16x16x32_bf16 v[2:5], v[194:197], v[226:229], v[2:5]
	v_mfma_f32_16x16x32_bf16 v[2:5], v[198:201], v[230:233], v[2:5]
	v_mfma_f32_16x16x32_bf16 v[6:9], v[186:189], v[226:229], v[6:9]
	v_mfma_f32_16x16x32_bf16 v[6:9], v[190:193], v[230:233], v[6:9]
	s_setprio 0
	s_nop 0
	s_add_i32 s67, s67, 2
	s_nop 0
	s_add_u32 s30, s30, 0x100
	s_addc_u32 s31, s31, 0
	s_cmp_gt_u32 s67, 13
	s_cbranch_scc1 .LBB0_181

.LBB0_587:
	s_add_u32 s4, s36, s38
	s_addc_u32 s5, s37, s39
	s_add_u32 s4, s4, 0x100
	s_addc_u32 s5, s5, 0
	s_add_u32 s72, s65, s38
	s_addc_u32 s73, s66, s39
	s_nop 0
	s_add_i32 s74, 0, 0x10000
	v_add_u32_e32 v3, s74, v213
	s_nop 0
	ds_read_b128 v[134:137], v3
	ds_read_b128 v[138:141], v3 offset:1024
	ds_read_b128 v[142:145], v3 offset:2048
	ds_read_b128 v[146:149], v3 offset:3072
	v_add_u32_e32 v3, s63, v213
	s_nop 0
	ds_read_b128 v[150:153], v3
	ds_read_b128 v[154:157], v3 offset:1024
	ds_read_b128 v[158:161], v3 offset:2048
	ds_read_b128 v[162:165], v3 offset:3072
	s_cmpk_eq_i32 s38, 0x700
	s_cselect_b32 s41, s3, s5
	s_cselect_b32 s40, s23, s4
	s_cselect_b32 s5, s25, s73
	s_cselect_b32 s4, s64, s72
	s_nop 0
	v_lshl_add_u64 v[4:5], v[170:171], 0, s[38:39]
	s_add_i32 m0, s31, 0xc000
	ds_read_b128 v[166:169], v217
	ds_read_b128 v[176:179], v217 offset:1024
	ds_read_b128 v[180:183], v217 offset:2048
	ds_read_b128 v[184:187], v217 offset:3072
	ds_read_b128 v[188:191], v217 offset:4096
	ds_read_b128 v[192:195], v217 offset:5120
	ds_read_b128 v[218:221], v217 offset:6144
	ds_read_b128 v[222:225], v217 offset:7168
	global_load_lds_dwordx4 v[4:5], off
	v_lshl_add_u64 v[4:5], v[172:173], 0, s[38:39]
	s_add_i32 m0, s31, 0xe000
	s_nop 0
	s_nop 0
	global_load_lds_dwordx4 v[4:5], off
	s_waitcnt vmcnt(8)
	s_waitcnt lgkmcnt(0)
	s_barrier
	s_setprio 1
	v_mfma_f32_16x16x32_bf16 v[130:133], v[134:137], v[166:169], v[130:133]
	v_mfma_f32_16x16x32_bf16 v[130:133], v[138:141], v[176:179], v[130:133]
	v_mfma_f32_16x16x32_bf16 v[126:129], v[142:145], v[166:169], v[126:129]
	v_mfma_f32_16x16x32_bf16 v[126:129], v[146:149], v[176:179], v[126:129]
	v_mfma_f32_16x16x32_bf16 v[110:113], v[142:145], v[180:183], v[110:113]
	v_mfma_f32_16x16x32_bf16 v[110:113], v[146:149], v[184:187], v[110:113]
	v_mfma_f32_16x16x32_bf16 v[114:117], v[134:137], v[180:183], v[114:117]
	v_mfma_f32_16x16x32_bf16 v[114:117], v[138:141], v[184:187], v[114:117]
	v_mfma_f32_16x16x32_bf16 v[98:101], v[134:137], v[188:191], v[98:101]
	v_mfma_f32_16x16x32_bf16 v[98:101], v[138:141], v[192:195], v[98:101]
	v_mfma_f32_16x16x32_bf16 v[94:97], v[142:145], v[188:191], v[94:97]
	v_mfma_f32_16x16x32_bf16 v[94:97], v[146:149], v[192:195], v[94:97]
	v_mfma_f32_16x16x32_bf16 v[78:81], v[142:145], v[218:221], v[78:81]
	v_mfma_f32_16x16x32_bf16 v[78:81], v[146:149], v[222:225], v[78:81]
	v_mfma_f32_16x16x32_bf16 v[82:85], v[134:137], v[218:221], v[82:85]
	v_mfma_f32_16x16x32_bf16 v[82:85], v[138:141], v[222:225], v[82:85]
	v_mfma_f32_16x16x32_bf16 v[122:125], v[150:153], v[166:169], v[122:125]
	v_mfma_f32_16x16x32_bf16 v[122:125], v[154:157], v[176:179], v[122:125]
	v_mfma_f32_16x16x32_bf16 v[118:121], v[158:161], v[166:169], v[118:121]
	v_mfma_f32_16x16x32_bf16 v[118:121], v[162:165], v[176:179], v[118:121]
	v_mfma_f32_16x16x32_bf16 v[102:105], v[158:161], v[180:183], v[102:105]
	v_mfma_f32_16x16x32_bf16 v[102:105], v[162:165], v[184:187], v[102:105]
	v_mfma_f32_16x16x32_bf16 v[106:109], v[150:153], v[180:183], v[106:109]
	v_mfma_f32_16x16x32_bf16 v[106:109], v[154:157], v[184:187], v[106:109]
	v_mfma_f32_16x16x32_bf16 v[90:93], v[150:153], v[188:191], v[90:93]
	v_mfma_f32_16x16x32_bf16 v[90:93], v[154:157], v[192:195], v[90:93]
	v_mfma_f32_16x16x32_bf16 v[86:89], v[158:161], v[188:191], v[86:89]
	v_mfma_f32_16x16x32_bf16 v[86:89], v[162:165], v[192:195], v[86:89]
	s_setprio 2
	s_barrier
	v_mfma_f32_16x16x32_bf16 v[70:73], v[158:161], v[218:221], v[70:73]
	v_mfma_f32_16x16x32_bf16 v[70:73], v[162:165], v[222:225], v[70:73]
	v_mfma_f32_16x16x32_bf16 v[74:77], v[150:153], v[218:221], v[74:77]
	v_mfma_f32_16x16x32_bf16 v[74:77], v[154:157], v[222:225], v[74:77]
	s_setprio 0
	s_nop 0
	s_add_i32 s72, s74, s33
	s_nop 0
	v_lshl_add_u64 v[196:197], s[4:5], 0, v[200:201]
	s_mov_b32 m0, s72
	s_nop 0
	ds_read_b128 v[166:169], v217 offset:16384
	ds_read_b128 v[176:179], v217 offset:17408
	ds_read_b128 v[180:183], v217 offset:18432
	ds_read_b128 v[184:187], v217 offset:19456
	ds_read_b128 v[188:191], v217 offset:20480
	ds_read_b128 v[192:195], v217 offset:21504
	ds_read_b128 v[218:221], v217 offset:22528
	ds_read_b128 v[222:225], v217 offset:23552
	global_load_lds_dwordx4 v[196:197], off
	s_add_i32 m0, s72, 0x2000
	s_add_u32 s72, s4, 0x40000
	v_lshl_add_u64 v[210:211], s[4:5], 0, v[204:205]
	s_addc_u32 s73, s5, 0
	s_add_i32 s74, s63, s33
	global_load_lds_dwordx4 v[210:211], off
	v_lshl_add_u64 v[4:5], s[72:73], 0, v[200:201]
	s_mov_b32 m0, s74
	s_nop 0
	v_lshl_add_u64 v[226:227], s[40:41], 0, v[198:199]
	global_load_lds_dwordx4 v[4:5], off
	v_lshl_add_u64 v[4:5], s[72:73], 0, v[204:205]
	s_add_i32 m0, s74, 0x2000
	v_lshl_add_u64 v[230:231], s[40:41], 0, v[202:203]
	global_load_lds_dwordx4 v[4:5], off
	s_mov_b32 m0, s31
	s_nop 0
	global_load_lds_dwordx4 v[226:227], off
	s_mov_b32 m0, s42
	s_nop 0
	global_load_lds_dwordx4 v[230:231], off
	s_waitcnt vmcnt(8)
	s_waitcnt lgkmcnt(0)
	s_barrier
	s_setprio 1
	v_mfma_f32_16x16x32_bf16 v[66:69], v[134:137], v[166:169], v[66:69]
	v_mfma_f32_16x16x32_bf16 v[66:69], v[138:141], v[176:179], v[66:69]
	v_mfma_f32_16x16x32_bf16 v[62:65], v[142:145], v[166:169], v[62:65]
	v_mfma_f32_16x16x32_bf16 v[62:65], v[146:149], v[176:179], v[62:65]
	v_mfma_f32_16x16x32_bf16 v[46:49], v[142:145], v[180:183], v[46:49]
	v_mfma_f32_16x16x32_bf16 v[46:49], v[146:149], v[184:187], v[46:49]
	v_mfma_f32_16x16x32_bf16 v[50:53], v[134:137], v[180:183], v[50:53]
	v_mfma_f32_16x16x32_bf16 v[50:53], v[138:141], v[184:187], v[50:53]
	v_mfma_f32_16x16x32_bf16 v[34:37], v[134:137], v[188:191], v[34:37]
	v_mfma_f32_16x16x32_bf16 v[34:37], v[138:141], v[192:195], v[34:37]
	v_mfma_f32_16x16x32_bf16 v[30:33], v[142:145], v[188:191], v[30:33]
	v_mfma_f32_16x16x32_bf16 v[30:33], v[146:149], v[192:195], v[30:33]
	v_mfma_f32_16x16x32_bf16 v[14:17], v[142:145], v[218:221], v[14:17]
	v_mfma_f32_16x16x32_bf16 v[14:17], v[146:149], v[222:225], v[14:17]
	v_mfma_f32_16x16x32_bf16 v[18:21], v[134:137], v[218:221], v[18:21]
	v_mfma_f32_16x16x32_bf16 v[18:21], v[138:141], v[222:225], v[18:21]
	v_mfma_f32_16x16x32_bf16 v[58:61], v[150:153], v[166:169], v[58:61]
	v_mfma_f32_16x16x32_bf16 v[58:61], v[154:157], v[176:179], v[58:61]
	v_mfma_f32_16x16x32_bf16 v[54:57], v[158:161], v[166:169], v[54:57]
	v_mfma_f32_16x16x32_bf16 v[54:57], v[162:165], v[176:179], v[54:57]
	v_mfma_f32_16x16x32_bf16 v[38:41], v[158:161], v[180:183], v[38:41]
	v_mfma_f32_16x16x32_bf16 v[38:41], v[162:165], v[184:187], v[38:41]
	v_mfma_f32_16x16x32_bf16 v[42:45], v[150:153], v[180:183], v[42:45]
	v_mfma_f32_16x16x32_bf16 v[42:45], v[154:157], v[184:187], v[42:45]
	v_mfma_f32_16x16x32_bf16 v[26:29], v[150:153], v[188:191], v[26:29]
	v_mfma_f32_16x16x32_bf16 v[26:29], v[154:157], v[192:195], v[26:29]
	v_mfma_f32_16x16x32_bf16 v[22:25], v[158:161], v[188:191], v[22:25]
	v_mfma_f32_16x16x32_bf16 v[22:25], v[162:165], v[192:195], v[22:25]
	s_setprio 2
	s_barrier
	v_mfma_f32_16x16x32_bf16 v[4:7], v[158:161], v[218:221], v[6:9]
	v_mfma_f32_16x16x32_bf16 v[4:7], v[162:165], v[222:225], v[4:7]
	v_mfma_f32_16x16x32_bf16 v[10:13], v[150:153], v[218:221], v[10:13]
	v_mfma_f32_16x16x32_bf16 v[10:13], v[154:157], v[222:225], v[10:13]
	s_setprio 0
	s_nop 0
	s_add_i32 s72, 0, 0x18000
	v_add_u32_e32 v3, s72, v213
	s_nop 0
	s_add_i32 s73, 0, 0x1c000
	ds_read_b128 v[134:137], v3
	ds_read_b128 v[138:141], v3 offset:1024
	ds_read_b128 v[142:145], v3 offset:2048
	ds_read_b128 v[146:149], v3 offset:3072
	v_add_u32_e32 v3, s73, v213
	s_nop 0
	ds_read_b128 v[150:153], v3
	ds_read_b128 v[154:157], v3 offset:1024
	ds_read_b128 v[158:161], v3 offset:2048
	ds_read_b128 v[162:165], v3 offset:3072
	s_add_u32 s40, s40, 0x40000
	s_addc_u32 s41, s41, 0
	s_mov_b32 m0, s43
	v_lshl_add_u64 v[8:9], s[40:41], 0, v[198:199]
	ds_read_b128 v[166:169], v217 offset:32768
	ds_read_b128 v[176:179], v217 offset:33792
	ds_read_b128 v[180:183], v217 offset:34816
	ds_read_b128 v[184:187], v217 offset:35840
	ds_read_b128 v[188:191], v217 offset:36864
	ds_read_b128 v[192:195], v217 offset:37888
	ds_read_b128 v[218:221], v217 offset:38912
	ds_read_b128 v[222:225], v217 offset:39936
	global_load_lds_dwordx4 v[8:9], off
	v_lshl_add_u64 v[8:9], s[40:41], 0, v[202:203]
	s_mov_b32 m0, s44
	s_nop 0
	global_load_lds_dwordx4 v[8:9], off
	s_waitcnt vmcnt(8)
	s_waitcnt lgkmcnt(0)
	s_barrier
	s_setprio 1
	v_mfma_f32_16x16x32_bf16 v[130:133], v[134:137], v[166:169], v[130:133]
	v_mfma_f32_16x16x32_bf16 v[130:133], v[138:141], v[176:179], v[130:133]
	v_mfma_f32_16x16x32_bf16 v[126:129], v[142:145], v[166:169], v[126:129]
	v_mfma_f32_16x16x32_bf16 v[126:129], v[146:149], v[176:179], v[126:129]
	v_mfma_f32_16x16x32_bf16 v[110:113], v[142:145], v[180:183], v[110:113]
	v_mfma_f32_16x16x32_bf16 v[110:113], v[146:149], v[184:187], v[110:113]
	v_mfma_f32_16x16x32_bf16 v[114:117], v[134:137], v[180:183], v[114:117]
	v_mfma_f32_16x16x32_bf16 v[114:117], v[138:141], v[184:187], v[114:117]
	v_mfma_f32_16x16x32_bf16 v[98:101], v[134:137], v[188:191], v[98:101]
	v_mfma_f32_16x16x32_bf16 v[98:101], v[138:141], v[192:195], v[98:101]
	v_mfma_f32_16x16x32_bf16 v[94:97], v[142:145], v[188:191], v[94:97]
	v_mfma_f32_16x16x32_bf16 v[94:97], v[146:149], v[192:195], v[94:97]
	v_mfma_f32_16x16x32_bf16 v[78:81], v[142:145], v[218:221], v[78:81]
	v_mfma_f32_16x16x32_bf16 v[78:81], v[146:149], v[222:225], v[78:81]
	v_mfma_f32_16x16x32_bf16 v[82:85], v[134:137], v[218:221], v[82:85]
	v_mfma_f32_16x16x32_bf16 v[82:85], v[138:141], v[222:225], v[82:85]
	v_mfma_f32_16x16x32_bf16 v[122:125], v[150:153], v[166:169], v[122:125]
	v_mfma_f32_16x16x32_bf16 v[122:125], v[154:157], v[176:179], v[122:125]
	v_mfma_f32_16x16x32_bf16 v[118:121], v[158:161], v[166:169], v[118:121]
	v_mfma_f32_16x16x32_bf16 v[118:121], v[162:165], v[176:179], v[118:121]
	v_mfma_f32_16x16x32_bf16 v[102:105], v[158:161], v[180:183], v[102:105]
	v_mfma_f32_16x16x32_bf16 v[102:105], v[162:165], v[184:187], v[102:105]
	v_mfma_f32_16x16x32_bf16 v[106:109], v[150:153], v[180:183], v[106:109]
	v_mfma_f32_16x16x32_bf16 v[106:109], v[154:157], v[184:187], v[106:109]
	v_mfma_f32_16x16x32_bf16 v[90:93], v[150:153], v[188:191], v[90:93]
	v_mfma_f32_16x16x32_bf16 v[90:93], v[154:157], v[192:195], v[90:93]
	v_mfma_f32_16x16x32_bf16 v[86:89], v[158:161], v[188:191], v[86:89]
	v_mfma_f32_16x16x32_bf16 v[86:89], v[162:165], v[192:195], v[86:89]
	s_setprio 2
	s_barrier
	v_mfma_f32_16x16x32_bf16 v[70:73], v[158:161], v[218:221], v[70:73]
	v_mfma_f32_16x16x32_bf16 v[70:73], v[162:165], v[222:225], v[70:73]
	v_mfma_f32_16x16x32_bf16 v[74:77], v[150:153], v[218:221], v[74:77]
	v_mfma_f32_16x16x32_bf16 v[74:77], v[154:157], v[222:225], v[74:77]
	s_setprio 0
	s_nop 0
	s_add_i32 s40, s72, s33
	s_nop 0
	v_lshl_add_u64 v[8:9], v[196:197], 0, s[10:11]
	s_mov_b32 m0, s40
	s_nop 0
	ds_read_b128 v[166:169], v217 offset:49152
	ds_read_b128 v[176:179], v217 offset:50176
	ds_read_b128 v[180:183], v217 offset:51200
	ds_read_b128 v[184:187], v217 offset:52224
	ds_read_b128 v[188:191], v217 offset:53248
	ds_read_b128 v[192:195], v217 offset:54272
	ds_read_b128 v[218:221], v217 offset:55296
	ds_read_b128 v[222:225], v217 offset:56320
	global_load_lds_dwordx4 v[8:9], off
	s_add_i32 m0, s40, 0x2000
	s_add_u32 s4, s4, 0x40080
	v_lshl_add_u64 v[8:9], v[210:211], 0, s[10:11]
	s_addc_u32 s5, s5, 0
	s_add_i32 s40, s73, s33
	global_load_lds_dwordx4 v[8:9], off
	v_lshl_add_u64 v[8:9], s[4:5], 0, v[200:201]
	s_mov_b32 m0, s40
	s_nop 0
	global_load_lds_dwordx4 v[8:9], off
	v_lshl_add_u64 v[8:9], s[4:5], 0, v[204:205]
	s_add_i32 m0, s40, 0x2000
	s_nop 0
	s_nop 0
	global_load_lds_dwordx4 v[8:9], off
	v_lshl_add_u64 v[8:9], v[226:227], 0, s[10:11]
	s_mov_b32 m0, s47
	s_nop 0
	global_load_lds_dwordx4 v[8:9], off
	v_lshl_add_u64 v[8:9], v[230:231], 0, s[10:11]
	s_mov_b32 m0, s48
	s_nop 0
	global_load_lds_dwordx4 v[8:9], off
	s_waitcnt vmcnt(8)
	s_waitcnt lgkmcnt(0)
	s_barrier
	s_setprio 1
	v_mfma_f32_16x16x32_bf16 v[66:69], v[134:137], v[166:169], v[66:69]
	v_mfma_f32_16x16x32_bf16 v[66:69], v[138:141], v[176:179], v[66:69]
	v_mfma_f32_16x16x32_bf16 v[62:65], v[142:145], v[166:169], v[62:65]
	v_mfma_f32_16x16x32_bf16 v[62:65], v[146:149], v[176:179], v[62:65]
	v_mfma_f32_16x16x32_bf16 v[46:49], v[142:145], v[180:183], v[46:49]
	v_mfma_f32_16x16x32_bf16 v[46:49], v[146:149], v[184:187], v[46:49]
	v_mfma_f32_16x16x32_bf16 v[50:53], v[134:137], v[180:183], v[50:53]
	v_mfma_f32_16x16x32_bf16 v[50:53], v[138:141], v[184:187], v[50:53]
	v_mfma_f32_16x16x32_bf16 v[34:37], v[134:137], v[188:191], v[34:37]
	v_mfma_f32_16x16x32_bf16 v[34:37], v[138:141], v[192:195], v[34:37]
	v_mfma_f32_16x16x32_bf16 v[30:33], v[142:145], v[188:191], v[30:33]
	v_mfma_f32_16x16x32_bf16 v[30:33], v[146:149], v[192:195], v[30:33]
	v_mfma_f32_16x16x32_bf16 v[14:17], v[142:145], v[218:221], v[14:17]
	v_mfma_f32_16x16x32_bf16 v[14:17], v[146:149], v[222:225], v[14:17]
	v_mfma_f32_16x16x32_bf16 v[18:21], v[134:137], v[218:221], v[18:21]
	v_mfma_f32_16x16x32_bf16 v[18:21], v[138:141], v[222:225], v[18:21]
	v_mfma_f32_16x16x32_bf16 v[58:61], v[150:153], v[166:169], v[58:61]
	v_mfma_f32_16x16x32_bf16 v[58:61], v[154:157], v[176:179], v[58:61]
	v_mfma_f32_16x16x32_bf16 v[54:57], v[158:161], v[166:169], v[54:57]
	v_mfma_f32_16x16x32_bf16 v[54:57], v[162:165], v[176:179], v[54:57]
	v_mfma_f32_16x16x32_bf16 v[42:45], v[150:153], v[180:183], v[42:45]
	v_mfma_f32_16x16x32_bf16 v[42:45], v[154:157], v[184:187], v[42:45]
	v_mfma_f32_16x16x32_bf16 v[38:41], v[158:161], v[180:183], v[38:41]
	v_mfma_f32_16x16x32_bf16 v[38:41], v[162:165], v[184:187], v[38:41]
	v_mfma_f32_16x16x32_bf16 v[26:29], v[150:153], v[188:191], v[26:29]
	v_mfma_f32_16x16x32_bf16 v[26:29], v[154:157], v[192:195], v[26:29]
	v_mfma_f32_16x16x32_bf16 v[22:25], v[158:161], v[188:191], v[22:25]
	v_mfma_f32_16x16x32_bf16 v[22:25], v[162:165], v[192:195], v[22:25]
	s_setprio 2
	s_barrier
	v_mfma_f32_16x16x32_bf16 v[8:11], v[150:153], v[218:221], v[10:13]
	v_mfma_f32_16x16x32_bf16 v[10:13], v[154:157], v[222:225], v[8:11]
	v_mfma_f32_16x16x32_bf16 v[4:7], v[158:161], v[218:221], v[4:7]
	v_mfma_f32_16x16x32_bf16 v[6:9], v[162:165], v[222:225], v[4:7]
	s_setprio 0
	s_nop 0
	s_add_i32 s67, s67, 2
	s_nop 0
	s_add_u32 s38, s38, 0x100
	s_addc_u32 s39, s39, 0
	s_cmp_gt_u32 s67, 13
	s_cbranch_scc1 .LBB0_590

.LBB0_760:
	ds_read_b128 v[114:117], v232
	ds_read_b128 v[118:121], v232 offset:1024
	ds_read_b128 v[130:133], v232 offset:2048
	ds_read_b128 v[138:141], v232 offset:3072
	ds_read_b128 v[146:149], v233
	ds_read_b128 v[150:153], v233 offset:1024
	ds_read_b128 v[154:157], v233 offset:2048
	ds_read_b128 v[158:161], v233 offset:3072
	s_add_u32 s30, s28, 0xfffc0080
	s_addc_u32 s31, s29, -1
	s_cmp_eq_u32 s47, 12
	s_cselect_b32 s35, s3, s31
	s_cselect_b32 s34, s17, s30
	s_cselect_b32 s31, s19, s46
	s_cselect_b32 s30, s27, s45
	v_lshl_add_u64 v[206:207], s[28:29], 0, v[202:203]
	s_add_i32 m0, s36, 0xc000
	ds_read_b128 v[162:165], v234
	ds_read_b128 v[166:169], v234 offset:1024
	ds_read_b128 v[170:173], v234 offset:2048
	ds_read_b128 v[174:177], v234 offset:3072
	ds_read_b128 v[178:181], v234 offset:4096
	ds_read_b128 v[182:185], v234 offset:5120
	ds_read_b128 v[186:189], v234 offset:6144
	ds_read_b128 v[190:193], v234 offset:7168
	global_load_lds_dwordx4 v[206:207], off
	v_lshl_add_u64 v[206:207], s[28:29], 0, v[204:205]
	s_add_i32 m0, s36, 0xe000
	s_nop 0
	s_nop 0
	global_load_lds_dwordx4 v[206:207], off
	s_waitcnt vmcnt(8)
	s_waitcnt lgkmcnt(0)
	s_barrier
	s_setprio 1
	v_mfma_f32_16x16x32_bf16 v[142:145], v[114:117], v[162:165], v[142:145]
	v_mfma_f32_16x16x32_bf16 v[142:145], v[118:121], v[166:169], v[142:145]
	v_mfma_f32_16x16x32_bf16 v[134:137], v[130:133], v[162:165], v[134:137]
	v_mfma_f32_16x16x32_bf16 v[134:137], v[138:141], v[166:169], v[134:137]
	v_mfma_f32_16x16x32_bf16 v[106:109], v[130:133], v[170:173], v[106:109]
	v_mfma_f32_16x16x32_bf16 v[106:109], v[138:141], v[174:177], v[106:109]
	v_mfma_f32_16x16x32_bf16 v[110:113], v[114:117], v[170:173], v[110:113]
	v_mfma_f32_16x16x32_bf16 v[110:113], v[118:121], v[174:177], v[110:113]
	v_mfma_f32_16x16x32_bf16 v[94:97], v[114:117], v[178:181], v[94:97]
	v_mfma_f32_16x16x32_bf16 v[94:97], v[118:121], v[182:185], v[94:97]
	v_mfma_f32_16x16x32_bf16 v[90:93], v[130:133], v[178:181], v[90:93]
	v_mfma_f32_16x16x32_bf16 v[90:93], v[138:141], v[182:185], v[90:93]
	v_mfma_f32_16x16x32_bf16 v[74:77], v[130:133], v[186:189], v[74:77]
	v_mfma_f32_16x16x32_bf16 v[74:77], v[138:141], v[190:193], v[74:77]
	v_mfma_f32_16x16x32_bf16 v[78:81], v[114:117], v[186:189], v[78:81]
	v_mfma_f32_16x16x32_bf16 v[78:81], v[118:121], v[190:193], v[78:81]
	v_mfma_f32_16x16x32_bf16 v[126:129], v[146:149], v[162:165], v[126:129]
	v_mfma_f32_16x16x32_bf16 v[126:129], v[150:153], v[166:169], v[126:129]
	v_mfma_f32_16x16x32_bf16 v[122:125], v[154:157], v[162:165], v[122:125]
	v_mfma_f32_16x16x32_bf16 v[122:125], v[158:161], v[166:169], v[122:125]
	v_mfma_f32_16x16x32_bf16 v[98:101], v[154:157], v[170:173], v[98:101]
	v_mfma_f32_16x16x32_bf16 v[98:101], v[158:161], v[174:177], v[98:101]
	v_mfma_f32_16x16x32_bf16 v[102:105], v[146:149], v[170:173], v[102:105]
	v_mfma_f32_16x16x32_bf16 v[102:105], v[150:153], v[174:177], v[102:105]
	v_mfma_f32_16x16x32_bf16 v[86:89], v[146:149], v[178:181], v[86:89]
	v_mfma_f32_16x16x32_bf16 v[86:89], v[150:153], v[182:185], v[86:89]
	v_mfma_f32_16x16x32_bf16 v[82:85], v[154:157], v[178:181], v[82:85]
	v_mfma_f32_16x16x32_bf16 v[82:85], v[158:161], v[182:185], v[82:85]
	s_setprio 2
	s_barrier
	v_mfma_f32_16x16x32_bf16 v[66:69], v[154:157], v[186:189], v[66:69]
	v_mfma_f32_16x16x32_bf16 v[66:69], v[158:161], v[190:193], v[66:69]
	v_mfma_f32_16x16x32_bf16 v[70:73], v[146:149], v[186:189], v[70:73]
	v_mfma_f32_16x16x32_bf16 v[70:73], v[150:153], v[190:193], v[70:73]
	s_setprio 0
	s_nop 0
	s_add_i32 s48, s43, s33
	s_nop 0
	v_lshl_add_u64 v[206:207], s[30:31], 0, v[196:197]
	s_mov_b32 m0, s48
	s_nop 0
	ds_read_b128 v[162:165], v234 offset:16384
	ds_read_b128 v[166:169], v234 offset:17408
	ds_read_b128 v[170:173], v234 offset:18432
	ds_read_b128 v[174:177], v234 offset:19456
	ds_read_b128 v[178:181], v234 offset:20480
	ds_read_b128 v[182:185], v234 offset:21504
	ds_read_b128 v[186:189], v234 offset:22528
	ds_read_b128 v[190:193], v234 offset:23552
	global_load_lds_dwordx4 v[206:207], off
	s_add_i32 m0, s48, 0x2000
	s_add_u32 s48, s30, 0x40000
	v_lshl_add_u64 v[208:209], s[30:31], 0, v[200:201]
	s_addc_u32 s49, s31, 0
	s_add_i32 s50, s44, s33
	global_load_lds_dwordx4 v[208:209], off
	v_lshl_add_u64 v[210:211], s[48:49], 0, v[196:197]
	s_mov_b32 m0, s50
	s_nop 0
	v_lshl_add_u64 v[212:213], s[34:35], 0, v[198:199]
	global_load_lds_dwordx4 v[210:211], off
	v_lshl_add_u64 v[210:211], s[48:49], 0, v[200:201]
	s_add_i32 m0, s50, 0x2000
	s_nop 0
	s_nop 0
	global_load_lds_dwordx4 v[210:211], off
	v_lshl_add_u64 v[210:211], s[34:35], 0, v[194:195]
	s_mov_b32 m0, s36
	s_nop 0
	global_load_lds_dwordx4 v[210:211], off
	s_mov_b32 m0, s37
	s_nop 0
	global_load_lds_dwordx4 v[212:213], off
	s_waitcnt vmcnt(8)
	s_waitcnt lgkmcnt(0)
	s_barrier
	s_setprio 1
	v_mfma_f32_16x16x32_bf16 v[62:65], v[114:117], v[162:165], v[62:65]
	v_mfma_f32_16x16x32_bf16 v[62:65], v[118:121], v[166:169], v[62:65]
	v_mfma_f32_16x16x32_bf16 v[58:61], v[130:133], v[162:165], v[58:61]
	v_mfma_f32_16x16x32_bf16 v[58:61], v[138:141], v[166:169], v[58:61]
	v_mfma_f32_16x16x32_bf16 v[42:45], v[130:133], v[170:173], v[42:45]
	v_mfma_f32_16x16x32_bf16 v[42:45], v[138:141], v[174:177], v[42:45]
	v_mfma_f32_16x16x32_bf16 v[46:49], v[114:117], v[170:173], v[46:49]
	v_mfma_f32_16x16x32_bf16 v[46:49], v[118:121], v[174:177], v[46:49]
	v_mfma_f32_16x16x32_bf16 v[30:33], v[114:117], v[178:181], v[30:33]
	v_mfma_f32_16x16x32_bf16 v[30:33], v[118:121], v[182:185], v[30:33]
	v_mfma_f32_16x16x32_bf16 v[26:29], v[130:133], v[178:181], v[26:29]
	v_mfma_f32_16x16x32_bf16 v[26:29], v[138:141], v[182:185], v[26:29]
	v_mfma_f32_16x16x32_bf16 v[10:13], v[130:133], v[186:189], v[10:13]
	v_mfma_f32_16x16x32_bf16 v[10:13], v[138:141], v[190:193], v[10:13]
	v_mfma_f32_16x16x32_bf16 v[14:17], v[114:117], v[186:189], v[14:17]
	v_mfma_f32_16x16x32_bf16 v[14:17], v[118:121], v[190:193], v[14:17]
	v_mfma_f32_16x16x32_bf16 v[54:57], v[146:149], v[162:165], v[54:57]
	v_mfma_f32_16x16x32_bf16 v[54:57], v[150:153], v[166:169], v[54:57]
	v_mfma_f32_16x16x32_bf16 v[50:53], v[154:157], v[162:165], v[50:53]
	v_mfma_f32_16x16x32_bf16 v[50:53], v[158:161], v[166:169], v[50:53]
	v_mfma_f32_16x16x32_bf16 v[34:37], v[154:157], v[170:173], v[34:37]
	v_mfma_f32_16x16x32_bf16 v[34:37], v[158:161], v[174:177], v[34:37]
	v_mfma_f32_16x16x32_bf16 v[38:41], v[146:149], v[170:173], v[38:41]
	v_mfma_f32_16x16x32_bf16 v[38:41], v[150:153], v[174:177], v[38:41]
	v_mfma_f32_16x16x32_bf16 v[22:25], v[146:149], v[178:181], v[22:25]
	v_mfma_f32_16x16x32_bf16 v[22:25], v[150:153], v[182:185], v[22:25]
	v_mfma_f32_16x16x32_bf16 v[18:21], v[154:157], v[178:181], v[18:21]
	v_mfma_f32_16x16x32_bf16 v[18:21], v[158:161], v[182:185], v[18:21]
	s_setprio 2
	s_barrier
	v_mfma_f32_16x16x32_bf16 v[2:5], v[154:157], v[186:189], v[2:5]
	v_mfma_f32_16x16x32_bf16 v[2:5], v[158:161], v[190:193], v[2:5]
	v_mfma_f32_16x16x32_bf16 v[6:9], v[146:149], v[186:189], v[6:9]
	v_mfma_f32_16x16x32_bf16 v[6:9], v[150:153], v[190:193], v[6:9]
	s_setprio 0
	s_nop 0
	s_add_i32 s48, 0, 0x18000
	s_add_i32 s49, 0, 0x1c000
	v_add_u32_e32 v138, s48, v230
	v_add_u32_e32 v158, s49, v230
	ds_read_b128 v[114:117], v138
	ds_read_b128 v[118:121], v138 offset:1024
	ds_read_b128 v[130:133], v138 offset:2048
	ds_read_b128 v[138:141], v138 offset:3072
	ds_read_b128 v[146:149], v158
	ds_read_b128 v[150:153], v158 offset:1024
	ds_read_b128 v[154:157], v158 offset:2048
	ds_read_b128 v[158:161], v158 offset:3072
	s_add_u32 s34, s34, 0x40000
	s_addc_u32 s35, s35, 0
	s_mov_b32 m0, s38
	v_lshl_add_u64 v[214:215], s[34:35], 0, v[194:195]
	ds_read_b128 v[162:165], v234 offset:32768
	ds_read_b128 v[166:169], v234 offset:33792
	ds_read_b128 v[170:173], v234 offset:34816
	ds_read_b128 v[174:177], v234 offset:35840
	ds_read_b128 v[178:181], v234 offset:36864
	ds_read_b128 v[182:185], v234 offset:37888
	ds_read_b128 v[186:189], v234 offset:38912
	ds_read_b128 v[190:193], v234 offset:39936
	global_load_lds_dwordx4 v[214:215], off
	v_lshl_add_u64 v[214:215], s[34:35], 0, v[198:199]
	s_mov_b32 m0, s39
	s_nop 0
	global_load_lds_dwordx4 v[214:215], off
	s_waitcnt vmcnt(8)
	s_waitcnt lgkmcnt(0)
	s_barrier
	s_setprio 1
	v_mfma_f32_16x16x32_bf16 v[142:145], v[114:117], v[162:165], v[142:145]
	v_mfma_f32_16x16x32_bf16 v[142:145], v[118:121], v[166:169], v[142:145]
	v_mfma_f32_16x16x32_bf16 v[134:137], v[130:133], v[162:165], v[134:137]
	v_mfma_f32_16x16x32_bf16 v[134:137], v[138:141], v[166:169], v[134:137]
	v_mfma_f32_16x16x32_bf16 v[106:109], v[130:133], v[170:173], v[106:109]
	v_mfma_f32_16x16x32_bf16 v[106:109], v[138:141], v[174:177], v[106:109]
	v_mfma_f32_16x16x32_bf16 v[110:113], v[114:117], v[170:173], v[110:113]
	v_mfma_f32_16x16x32_bf16 v[110:113], v[118:121], v[174:177], v[110:113]
	v_mfma_f32_16x16x32_bf16 v[94:97], v[114:117], v[178:181], v[94:97]
	v_mfma_f32_16x16x32_bf16 v[94:97], v[118:121], v[182:185], v[94:97]
	v_mfma_f32_16x16x32_bf16 v[90:93], v[130:133], v[178:181], v[90:93]
	v_mfma_f32_16x16x32_bf16 v[90:93], v[138:141], v[182:185], v[90:93]
	v_mfma_f32_16x16x32_bf16 v[74:77], v[130:133], v[186:189], v[74:77]
	v_mfma_f32_16x16x32_bf16 v[74:77], v[138:141], v[190:193], v[74:77]
	v_mfma_f32_16x16x32_bf16 v[78:81], v[114:117], v[186:189], v[78:81]
	v_mfma_f32_16x16x32_bf16 v[78:81], v[118:121], v[190:193], v[78:81]
	v_mfma_f32_16x16x32_bf16 v[126:129], v[146:149], v[162:165], v[126:129]
	v_mfma_f32_16x16x32_bf16 v[126:129], v[150:153], v[166:169], v[126:129]
	v_mfma_f32_16x16x32_bf16 v[122:125], v[154:157], v[162:165], v[122:125]
	v_mfma_f32_16x16x32_bf16 v[122:125], v[158:161], v[166:169], v[122:125]
	v_mfma_f32_16x16x32_bf16 v[98:101], v[154:157], v[170:173], v[98:101]
	v_mfma_f32_16x16x32_bf16 v[98:101], v[158:161], v[174:177], v[98:101]
	v_mfma_f32_16x16x32_bf16 v[102:105], v[146:149], v[170:173], v[102:105]
	v_mfma_f32_16x16x32_bf16 v[102:105], v[150:153], v[174:177], v[102:105]
	v_mfma_f32_16x16x32_bf16 v[86:89], v[146:149], v[178:181], v[86:89]
	v_mfma_f32_16x16x32_bf16 v[86:89], v[150:153], v[182:185], v[86:89]
	v_mfma_f32_16x16x32_bf16 v[82:85], v[154:157], v[178:181], v[82:85]
	v_mfma_f32_16x16x32_bf16 v[82:85], v[158:161], v[182:185], v[82:85]
	s_setprio 2
	s_barrier
	v_mfma_f32_16x16x32_bf16 v[66:69], v[154:157], v[186:189], v[66:69]
	v_mfma_f32_16x16x32_bf16 v[66:69], v[158:161], v[190:193], v[66:69]
	v_mfma_f32_16x16x32_bf16 v[70:73], v[146:149], v[186:189], v[70:73]
	v_mfma_f32_16x16x32_bf16 v[70:73], v[150:153], v[190:193], v[70:73]
	s_setprio 0
	s_nop 0
	s_add_i32 s34, s48, s33
	s_nop 0
	v_lshl_add_u64 v[206:207], v[206:207], 0, s[8:9]
	s_mov_b32 m0, s34
	s_nop 0
	ds_read_b128 v[162:165], v234 offset:49152
	ds_read_b128 v[166:169], v234 offset:50176
	ds_read_b128 v[170:173], v234 offset:51200
	ds_read_b128 v[174:177], v234 offset:52224
	ds_read_b128 v[178:181], v234 offset:53248
	ds_read_b128 v[182:185], v234 offset:54272
	ds_read_b128 v[186:189], v234 offset:55296
	ds_read_b128 v[190:193], v234 offset:56320
	global_load_lds_dwordx4 v[206:207], off
	s_add_i32 m0, s34, 0x2000
	s_add_u32 s30, s30, 0x40080
	v_lshl_add_u64 v[206:207], v[208:209], 0, s[8:9]
	s_addc_u32 s31, s31, 0
	s_add_i32 s34, s49, s33
	global_load_lds_dwordx4 v[206:207], off
	v_lshl_add_u64 v[206:207], s[30:31], 0, v[196:197]
	s_mov_b32 m0, s34
	s_nop 0
	global_load_lds_dwordx4 v[206:207], off
	v_lshl_add_u64 v[206:207], s[30:31], 0, v[200:201]
	s_add_i32 m0, s34, 0x2000
	s_nop 0
	s_nop 0
	global_load_lds_dwordx4 v[206:207], off
	v_lshl_add_u64 v[206:207], v[210:211], 0, s[8:9]
	s_mov_b32 m0, s40
	s_nop 0
	global_load_lds_dwordx4 v[206:207], off
	v_lshl_add_u64 v[206:207], v[212:213], 0, s[8:9]
	s_mov_b32 m0, s41
	s_nop 0
	global_load_lds_dwordx4 v[206:207], off
	s_waitcnt vmcnt(8)
	s_waitcnt lgkmcnt(0)
	s_barrier
	s_setprio 1
	v_mfma_f32_16x16x32_bf16 v[62:65], v[114:117], v[162:165], v[62:65]
	v_mfma_f32_16x16x32_bf16 v[62:65], v[118:121], v[166:169], v[62:65]
	v_mfma_f32_16x16x32_bf16 v[58:61], v[130:133], v[162:165], v[58:61]
	v_mfma_f32_16x16x32_bf16 v[58:61], v[138:141], v[166:169], v[58:61]
	v_mfma_f32_16x16x32_bf16 v[42:45], v[130:133], v[170:173], v[42:45]
	v_mfma_f32_16x16x32_bf16 v[42:45], v[138:141], v[174:177], v[42:45]
	v_mfma_f32_16x16x32_bf16 v[46:49], v[114:117], v[170:173], v[46:49]
	v_mfma_f32_16x16x32_bf16 v[46:49], v[118:121], v[174:177], v[46:49]
	v_mfma_f32_16x16x32_bf16 v[30:33], v[114:117], v[178:181], v[30:33]
	v_mfma_f32_16x16x32_bf16 v[30:33], v[118:121], v[182:185], v[30:33]
	v_mfma_f32_16x16x32_bf16 v[26:29], v[130:133], v[178:181], v[26:29]
	v_mfma_f32_16x16x32_bf16 v[26:29], v[138:141], v[182:185], v[26:29]
	v_mfma_f32_16x16x32_bf16 v[10:13], v[130:133], v[186:189], v[10:13]
	v_mfma_f32_16x16x32_bf16 v[10:13], v[138:141], v[190:193], v[10:13]
	v_mfma_f32_16x16x32_bf16 v[14:17], v[114:117], v[186:189], v[14:17]
	v_mfma_f32_16x16x32_bf16 v[14:17], v[118:121], v[190:193], v[14:17]
	v_mfma_f32_16x16x32_bf16 v[54:57], v[146:149], v[162:165], v[54:57]
	v_mfma_f32_16x16x32_bf16 v[54:57], v[150:153], v[166:169], v[54:57]
	v_mfma_f32_16x16x32_bf16 v[50:53], v[154:157], v[162:165], v[50:53]
	v_mfma_f32_16x16x32_bf16 v[50:53], v[158:161], v[166:169], v[50:53]
	v_mfma_f32_16x16x32_bf16 v[34:37], v[154:157], v[170:173], v[34:37]
	v_mfma_f32_16x16x32_bf16 v[34:37], v[158:161], v[174:177], v[34:37]
	v_mfma_f32_16x16x32_bf16 v[38:41], v[146:149], v[170:173], v[38:41]
	v_mfma_f32_16x16x32_bf16 v[38:41], v[150:153], v[174:177], v[38:41]
	v_mfma_f32_16x16x32_bf16 v[22:25], v[146:149], v[178:181], v[22:25]
	v_mfma_f32_16x16x32_bf16 v[22:25], v[150:153], v[182:185], v[22:25]
	v_mfma_f32_16x16x32_bf16 v[18:21], v[154:157], v[178:181], v[18:21]
	v_mfma_f32_16x16x32_bf16 v[18:21], v[158:161], v[182:185], v[18:21]
	s_setprio 2
	s_barrier
	v_mfma_f32_16x16x32_bf16 v[2:5], v[154:157], v[186:189], v[2:5]
	v_mfma_f32_16x16x32_bf16 v[2:5], v[158:161], v[190:193], v[2:5]
	v_mfma_f32_16x16x32_bf16 v[6:9], v[146:149], v[186:189], v[6:9]
	v_mfma_f32_16x16x32_bf16 v[6:9], v[150:153], v[190:193], v[6:9]
	s_setprio 0
	s_nop 0
	s_add_i32 s47, s47, 2
	s_nop 0
	s_add_u32 s28, s28, 0x100
	s_addc_u32 s29, s29, 0
	s_nop 0
	s_add_u32 s45, s45, 0x100
	s_addc_u32 s46, s46, 0
	s_cmp_gt_u32 s47, 13
	s_cbranch_scc0 .LBB0_760
	s_and_b64 vcc, exec, s[10:11]
	s_cbranch_vccz .LBB0_763
	s_barrier

.LBB0_945:
	ds_read_b128 v[154:157], v229
	ds_read_b128 v[158:161], v229 offset:1024
	ds_read_b128 v[162:165], v229 offset:2048
	ds_read_b128 v[166:169], v229 offset:3072
	s_add_u32 s22, s18, s20
	s_nop 0
	ds_read_b128 v[170:173], v229 offset:16384
	ds_read_b128 v[174:177], v229 offset:17408
	ds_read_b128 v[178:181], v229 offset:18432
	ds_read_b128 v[182:185], v229 offset:19456
	s_addc_u32 s23, s19, s21
	s_nop 0
	s_add_u32 s22, s22, 0x100
	s_addc_u32 s23, s23, 0
	s_add_u32 s45, s42, s20
	s_addc_u32 s46, s43, s21
	s_cmpk_eq_i32 s20, 0x700
	s_cselect_b32 s25, s9, s23
	s_cselect_b32 s24, s39, s22
	s_cselect_b32 s23, s40, s46
	s_cselect_b32 s22, s41, s45
	s_add_u32 s48, s18, s20
	s_addc_u32 s49, s19, s21
	s_add_i32 m0, s27, 0xc000
	ds_read_b128 v[186:189], v152
	ds_read_b128 v[190:193], v152 offset:1024
	ds_read_b128 v[194:197], v152 offset:2048
	ds_read_b128 v[198:201], v152 offset:3072
	ds_read_b128 v[202:205], v152 offset:4096
	ds_read_b128 v[206:209], v152 offset:5120
	ds_read_b128 v[210:213], v152 offset:6144
	ds_read_b128 v[214:217], v152 offset:7168
	global_load_lds_dwordx4 v138, s[48:49]
	s_add_i32 m0, s27, 0xe000
	s_nop 0
	s_nop 0
	global_load_lds_dwordx4 v140, s[48:49]
	s_waitcnt vmcnt(8)
	s_waitcnt lgkmcnt(0)
	s_barrier
	s_setprio 1
	v_mfma_f32_16x16x32_bf16 v[126:129], v[154:157], v[186:189], v[126:129]
	v_mfma_f32_16x16x32_bf16 v[126:129], v[158:161], v[190:193], v[126:129]
	v_mfma_f32_16x16x32_bf16 v[118:121], v[162:165], v[186:189], v[118:121]
	v_mfma_f32_16x16x32_bf16 v[118:121], v[166:169], v[190:193], v[118:121]
	v_mfma_f32_16x16x32_bf16 v[102:105], v[162:165], v[194:197], v[102:105]
	v_mfma_f32_16x16x32_bf16 v[102:105], v[166:169], v[198:201], v[102:105]
	v_mfma_f32_16x16x32_bf16 v[110:113], v[154:157], v[194:197], v[110:113]
	v_mfma_f32_16x16x32_bf16 v[110:113], v[158:161], v[198:201], v[110:113]
	v_mfma_f32_16x16x32_bf16 v[94:97], v[154:157], v[202:205], v[94:97]
	v_mfma_f32_16x16x32_bf16 v[94:97], v[158:161], v[206:209], v[94:97]
	v_mfma_f32_16x16x32_bf16 v[86:89], v[162:165], v[202:205], v[86:89]
	v_mfma_f32_16x16x32_bf16 v[86:89], v[166:169], v[206:209], v[86:89]
	v_mfma_f32_16x16x32_bf16 v[70:73], v[162:165], v[210:213], v[70:73]
	v_mfma_f32_16x16x32_bf16 v[70:73], v[166:169], v[214:217], v[70:73]
	v_mfma_f32_16x16x32_bf16 v[78:81], v[154:157], v[210:213], v[78:81]
	v_mfma_f32_16x16x32_bf16 v[78:81], v[158:161], v[214:217], v[78:81]
	v_mfma_f32_16x16x32_bf16 v[122:125], v[170:173], v[186:189], v[122:125]
	v_mfma_f32_16x16x32_bf16 v[122:125], v[174:177], v[190:193], v[122:125]
	v_mfma_f32_16x16x32_bf16 v[114:117], v[178:181], v[186:189], v[114:117]
	v_mfma_f32_16x16x32_bf16 v[114:117], v[182:185], v[190:193], v[114:117]
	v_mfma_f32_16x16x32_bf16 v[98:101], v[178:181], v[194:197], v[98:101]
	v_mfma_f32_16x16x32_bf16 v[98:101], v[182:185], v[198:201], v[98:101]
	v_mfma_f32_16x16x32_bf16 v[106:109], v[170:173], v[194:197], v[106:109]
	v_mfma_f32_16x16x32_bf16 v[106:109], v[174:177], v[198:201], v[106:109]
	v_mfma_f32_16x16x32_bf16 v[90:93], v[170:173], v[202:205], v[90:93]
	v_mfma_f32_16x16x32_bf16 v[90:93], v[174:177], v[206:209], v[90:93]
	v_mfma_f32_16x16x32_bf16 v[82:85], v[178:181], v[202:205], v[82:85]
	v_mfma_f32_16x16x32_bf16 v[82:85], v[182:185], v[206:209], v[82:85]
	s_setprio 2
	s_barrier
	v_mfma_f32_16x16x32_bf16 v[66:69], v[178:181], v[210:213], v[66:69]
	v_mfma_f32_16x16x32_bf16 v[66:69], v[182:185], v[214:217], v[66:69]
	v_mfma_f32_16x16x32_bf16 v[74:77], v[170:173], v[210:213], v[74:77]
	v_mfma_f32_16x16x32_bf16 v[74:77], v[174:177], v[214:217], v[74:77]
	s_setprio 0
	s_nop 0
	s_add_i32 s45, s35, s26
	s_nop 0
	s_add_u32 s50, s22, 0x80
	s_addc_u32 s51, s23, 0
	s_nop 0
	s_add_u32 s52, s24, 0x80
	s_addc_u32 s53, s25, 0
	s_mov_b32 m0, s45
	ds_read_b128 v[186:189], v152 offset:16384
	ds_read_b128 v[190:193], v152 offset:17408
	ds_read_b128 v[194:197], v152 offset:18432
	ds_read_b128 v[198:201], v152 offset:19456
	ds_read_b128 v[202:205], v152 offset:20480
	ds_read_b128 v[206:209], v152 offset:21504
	ds_read_b128 v[210:213], v152 offset:22528
	ds_read_b128 v[214:217], v152 offset:23552
	global_load_lds_dwordx4 v134, s[22:23]
	s_add_i32 m0, s45, 0x2000
	s_add_u32 s46, s22, 0x40000
	s_addc_u32 s47, s23, 0
	s_add_i32 s45, s36, s26
	global_load_lds_dwordx4 v130, s[22:23]
	s_mov_b32 m0, s45
	s_nop 0
	global_load_lds_dwordx4 v134, s[46:47]
	s_add_i32 m0, s45, 0x2000
	s_nop 0
	s_nop 0
	global_load_lds_dwordx4 v130, s[46:47]
	s_mov_b32 m0, s27
	s_nop 0
	global_load_lds_dwordx4 v136, s[24:25]
	s_mov_b32 m0, s28
	s_nop 0
	global_load_lds_dwordx4 v132, s[24:25]
	s_waitcnt vmcnt(8)
	s_waitcnt lgkmcnt(0)
	s_barrier
	s_setprio 1
	v_mfma_f32_16x16x32_bf16 v[62:65], v[154:157], v[186:189], v[62:65]
	v_mfma_f32_16x16x32_bf16 v[62:65], v[158:161], v[190:193], v[62:65]
	v_mfma_f32_16x16x32_bf16 v[54:57], v[162:165], v[186:189], v[54:57]
	v_mfma_f32_16x16x32_bf16 v[54:57], v[166:169], v[190:193], v[54:57]
	v_mfma_f32_16x16x32_bf16 v[38:41], v[162:165], v[194:197], v[38:41]
	v_mfma_f32_16x16x32_bf16 v[38:41], v[166:169], v[198:201], v[38:41]
	v_mfma_f32_16x16x32_bf16 v[46:49], v[154:157], v[194:197], v[46:49]
	v_mfma_f32_16x16x32_bf16 v[46:49], v[158:161], v[198:201], v[46:49]
	v_mfma_f32_16x16x32_bf16 v[30:33], v[154:157], v[202:205], v[30:33]
	v_mfma_f32_16x16x32_bf16 v[30:33], v[158:161], v[206:209], v[30:33]
	v_mfma_f32_16x16x32_bf16 v[22:25], v[162:165], v[202:205], v[22:25]
	v_mfma_f32_16x16x32_bf16 v[22:25], v[166:169], v[206:209], v[22:25]
	v_mfma_f32_16x16x32_bf16 v[6:9], v[162:165], v[210:213], v[6:9]
	v_mfma_f32_16x16x32_bf16 v[6:9], v[166:169], v[214:217], v[6:9]
	v_mfma_f32_16x16x32_bf16 v[14:17], v[154:157], v[210:213], v[14:17]
	v_mfma_f32_16x16x32_bf16 v[14:17], v[158:161], v[214:217], v[14:17]
	v_mfma_f32_16x16x32_bf16 v[58:61], v[170:173], v[186:189], v[58:61]
	v_mfma_f32_16x16x32_bf16 v[58:61], v[174:177], v[190:193], v[58:61]
	v_mfma_f32_16x16x32_bf16 v[50:53], v[178:181], v[186:189], v[50:53]
	v_mfma_f32_16x16x32_bf16 v[50:53], v[182:185], v[190:193], v[50:53]
	v_mfma_f32_16x16x32_bf16 v[34:37], v[178:181], v[194:197], v[34:37]
	v_mfma_f32_16x16x32_bf16 v[34:37], v[182:185], v[198:201], v[34:37]
	v_mfma_f32_16x16x32_bf16 v[42:45], v[170:173], v[194:197], v[42:45]
	v_mfma_f32_16x16x32_bf16 v[42:45], v[174:177], v[198:201], v[42:45]
	v_mfma_f32_16x16x32_bf16 v[26:29], v[170:173], v[202:205], v[26:29]
	v_mfma_f32_16x16x32_bf16 v[26:29], v[174:177], v[206:209], v[26:29]
	v_mfma_f32_16x16x32_bf16 v[18:21], v[178:181], v[202:205], v[18:21]
	v_mfma_f32_16x16x32_bf16 v[18:21], v[182:185], v[206:209], v[18:21]
	s_setprio 2
	s_barrier
	v_mfma_f32_16x16x32_bf16 v[2:5], v[178:181], v[210:213], v[2:5]
	v_mfma_f32_16x16x32_bf16 v[2:5], v[182:185], v[214:217], v[2:5]
	v_mfma_f32_16x16x32_bf16 v[10:13], v[170:173], v[210:213], v[10:13]
	v_mfma_f32_16x16x32_bf16 v[10:13], v[174:177], v[214:217], v[10:13]
	s_setprio 0
	s_nop 0
	s_add_i32 s45, 0, 0x18000
	s_add_i32 s46, 0, 0x1c000
	ds_read_b128 v[154:157], v229 offset:32768
	ds_read_b128 v[158:161], v229 offset:33792
	ds_read_b128 v[162:165], v229 offset:34816
	ds_read_b128 v[166:169], v229 offset:35840
	ds_read_b128 v[170:173], v229 offset:49152
	ds_read_b128 v[174:177], v229 offset:50176
	ds_read_b128 v[178:181], v229 offset:51200
	ds_read_b128 v[182:185], v229 offset:52224
	s_add_u32 s24, s24, 0x40000
	s_addc_u32 s25, s25, 0
	s_mov_b32 m0, s29
	ds_read_b128 v[186:189], v152 offset:32768
	ds_read_b128 v[190:193], v152 offset:33792
	ds_read_b128 v[194:197], v152 offset:34816
	ds_read_b128 v[198:201], v152 offset:35840
	ds_read_b128 v[202:205], v152 offset:36864
	ds_read_b128 v[206:209], v152 offset:37888
	ds_read_b128 v[210:213], v152 offset:38912
	ds_read_b128 v[214:217], v152 offset:39936
	global_load_lds_dwordx4 v136, s[24:25]
	s_mov_b32 m0, s30
	s_nop 0
	global_load_lds_dwordx4 v132, s[24:25]
	s_waitcnt vmcnt(8)
	s_waitcnt lgkmcnt(0)
	s_barrier
	s_setprio 1
	v_mfma_f32_16x16x32_bf16 v[126:129], v[154:157], v[186:189], v[126:129]
	v_mfma_f32_16x16x32_bf16 v[126:129], v[158:161], v[190:193], v[126:129]
	v_mfma_f32_16x16x32_bf16 v[118:121], v[162:165], v[186:189], v[118:121]
	v_mfma_f32_16x16x32_bf16 v[118:121], v[166:169], v[190:193], v[118:121]
	v_mfma_f32_16x16x32_bf16 v[102:105], v[162:165], v[194:197], v[102:105]
	v_mfma_f32_16x16x32_bf16 v[102:105], v[166:169], v[198:201], v[102:105]
	v_mfma_f32_16x16x32_bf16 v[110:113], v[154:157], v[194:197], v[110:113]
	v_mfma_f32_16x16x32_bf16 v[110:113], v[158:161], v[198:201], v[110:113]
	v_mfma_f32_16x16x32_bf16 v[94:97], v[154:157], v[202:205], v[94:97]
	v_mfma_f32_16x16x32_bf16 v[94:97], v[158:161], v[206:209], v[94:97]
	v_mfma_f32_16x16x32_bf16 v[86:89], v[162:165], v[202:205], v[86:89]
	v_mfma_f32_16x16x32_bf16 v[86:89], v[166:169], v[206:209], v[86:89]
	v_mfma_f32_16x16x32_bf16 v[70:73], v[162:165], v[210:213], v[70:73]
	v_mfma_f32_16x16x32_bf16 v[70:73], v[166:169], v[214:217], v[70:73]
	v_mfma_f32_16x16x32_bf16 v[78:81], v[154:157], v[210:213], v[78:81]
	v_mfma_f32_16x16x32_bf16 v[78:81], v[158:161], v[214:217], v[78:81]
	v_mfma_f32_16x16x32_bf16 v[122:125], v[170:173], v[186:189], v[122:125]
	v_mfma_f32_16x16x32_bf16 v[122:125], v[174:177], v[190:193], v[122:125]
	v_mfma_f32_16x16x32_bf16 v[114:117], v[178:181], v[186:189], v[114:117]
	v_mfma_f32_16x16x32_bf16 v[114:117], v[182:185], v[190:193], v[114:117]
	v_mfma_f32_16x16x32_bf16 v[98:101], v[178:181], v[194:197], v[98:101]
	v_mfma_f32_16x16x32_bf16 v[98:101], v[182:185], v[198:201], v[98:101]
	v_mfma_f32_16x16x32_bf16 v[106:109], v[170:173], v[194:197], v[106:109]
	v_mfma_f32_16x16x32_bf16 v[106:109], v[174:177], v[198:201], v[106:109]
	v_mfma_f32_16x16x32_bf16 v[90:93], v[170:173], v[202:205], v[90:93]
	v_mfma_f32_16x16x32_bf16 v[90:93], v[174:177], v[206:209], v[90:93]
	v_mfma_f32_16x16x32_bf16 v[82:85], v[178:181], v[202:205], v[82:85]
	v_mfma_f32_16x16x32_bf16 v[82:85], v[182:185], v[206:209], v[82:85]
	s_setprio 2
	s_barrier
	v_mfma_f32_16x16x32_bf16 v[66:69], v[178:181], v[210:213], v[66:69]
	v_mfma_f32_16x16x32_bf16 v[66:69], v[182:185], v[214:217], v[66:69]
	v_mfma_f32_16x16x32_bf16 v[74:77], v[170:173], v[210:213], v[74:77]
	v_mfma_f32_16x16x32_bf16 v[74:77], v[174:177], v[214:217], v[74:77]
	s_setprio 0
	s_nop 0
	s_add_i32 s24, s45, s26
	s_mov_b32 m0, s24
	ds_read_b128 v[186:189], v152 offset:49152
	ds_read_b128 v[190:193], v152 offset:50176
	ds_read_b128 v[194:197], v152 offset:51200
	ds_read_b128 v[198:201], v152 offset:52224
	ds_read_b128 v[202:205], v152 offset:53248
	ds_read_b128 v[206:209], v152 offset:54272
	ds_read_b128 v[210:213], v152 offset:55296
	ds_read_b128 v[214:217], v152 offset:56320
	global_load_lds_dwordx4 v134, s[50:51]
	s_add_i32 m0, s24, 0x2000
	s_add_u32 s22, s22, 0x40080
	s_addc_u32 s23, s23, 0
	s_add_i32 s24, s46, s26
	global_load_lds_dwordx4 v130, s[50:51]
	s_mov_b32 m0, s24
	s_nop 0
	global_load_lds_dwordx4 v134, s[22:23]
	s_add_i32 m0, s24, 0x2000
	s_nop 0
	s_nop 0
	global_load_lds_dwordx4 v130, s[22:23]
	s_mov_b32 m0, s33
	s_nop 0
	global_load_lds_dwordx4 v136, s[52:53]
	s_mov_b32 m0, s34
	s_nop 0
	global_load_lds_dwordx4 v132, s[52:53]
	s_waitcnt vmcnt(8)
	s_waitcnt lgkmcnt(0)
	s_barrier
	s_setprio 1
	v_mfma_f32_16x16x32_bf16 v[62:65], v[154:157], v[186:189], v[62:65]
	v_mfma_f32_16x16x32_bf16 v[62:65], v[158:161], v[190:193], v[62:65]
	v_mfma_f32_16x16x32_bf16 v[54:57], v[162:165], v[186:189], v[54:57]
	v_mfma_f32_16x16x32_bf16 v[54:57], v[166:169], v[190:193], v[54:57]
	v_mfma_f32_16x16x32_bf16 v[38:41], v[162:165], v[194:197], v[38:41]
	v_mfma_f32_16x16x32_bf16 v[38:41], v[166:169], v[198:201], v[38:41]
	v_mfma_f32_16x16x32_bf16 v[46:49], v[154:157], v[194:197], v[46:49]
	v_mfma_f32_16x16x32_bf16 v[46:49], v[158:161], v[198:201], v[46:49]
	v_mfma_f32_16x16x32_bf16 v[30:33], v[154:157], v[202:205], v[30:33]
	v_mfma_f32_16x16x32_bf16 v[30:33], v[158:161], v[206:209], v[30:33]
	v_mfma_f32_16x16x32_bf16 v[22:25], v[162:165], v[202:205], v[22:25]
	v_mfma_f32_16x16x32_bf16 v[22:25], v[166:169], v[206:209], v[22:25]
	v_mfma_f32_16x16x32_bf16 v[6:9], v[162:165], v[210:213], v[6:9]
	v_mfma_f32_16x16x32_bf16 v[6:9], v[166:169], v[214:217], v[6:9]
	v_mfma_f32_16x16x32_bf16 v[14:17], v[154:157], v[210:213], v[14:17]
	v_mfma_f32_16x16x32_bf16 v[14:17], v[158:161], v[214:217], v[14:17]
	v_mfma_f32_16x16x32_bf16 v[58:61], v[170:173], v[186:189], v[58:61]
	v_mfma_f32_16x16x32_bf16 v[58:61], v[174:177], v[190:193], v[58:61]
	v_mfma_f32_16x16x32_bf16 v[50:53], v[178:181], v[186:189], v[50:53]
	v_mfma_f32_16x16x32_bf16 v[50:53], v[182:185], v[190:193], v[50:53]
	v_mfma_f32_16x16x32_bf16 v[34:37], v[178:181], v[194:197], v[34:37]
	v_mfma_f32_16x16x32_bf16 v[34:37], v[182:185], v[198:201], v[34:37]
	v_mfma_f32_16x16x32_bf16 v[42:45], v[170:173], v[194:197], v[42:45]
	v_mfma_f32_16x16x32_bf16 v[42:45], v[174:177], v[198:201], v[42:45]
	v_mfma_f32_16x16x32_bf16 v[26:29], v[170:173], v[202:205], v[26:29]
	v_mfma_f32_16x16x32_bf16 v[26:29], v[174:177], v[206:209], v[26:29]
	v_mfma_f32_16x16x32_bf16 v[18:21], v[178:181], v[202:205], v[18:21]
	v_mfma_f32_16x16x32_bf16 v[18:21], v[182:185], v[206:209], v[18:21]
	s_setprio 2
	s_barrier
	v_mfma_f32_16x16x32_bf16 v[2:5], v[178:181], v[210:213], v[2:5]
	v_mfma_f32_16x16x32_bf16 v[2:5], v[182:185], v[214:217], v[2:5]
	v_mfma_f32_16x16x32_bf16 v[10:13], v[170:173], v[210:213], v[10:13]
	v_mfma_f32_16x16x32_bf16 v[10:13], v[174:177], v[214:217], v[10:13]
	s_setprio 0
	s_nop 0
	s_add_i32 s44, s44, 2
	s_nop 0
	s_add_u32 s20, s20, 0x100
	s_addc_u32 s21, s21, 0
	s_cmp_gt_u32 s44, 13
	s_cbranch_scc1 .LBB0_948

.LBB0_1018:
	s_add_u32 s4, s70, s56
	s_addc_u32 s5, s71, s57
	s_add_u32 s59, s70, s2
	s_addc_u32 s60, s71, s3
	s_nop 0
	s_add_i32 s61, 0, 0x10000
	s_cmp_eq_u32 s58, 40
	s_cselect_b32 s31, s1, s5
	s_cselect_b32 s30, s0, s4
	s_cselect_b32 s5, s15, s60
	s_cselect_b32 s4, s14, s59
	s_nop 0
	s_add_i32 s59, 0, 0x14000
	v_add_u32_e32 v154, s61, v140
	v_add_u32_e32 v170, s59, v140
	ds_read_b128 v[142:145], v154
	ds_read_b128 v[146:149], v154 offset:1024
	ds_read_b128 v[150:153], v154 offset:2048
	ds_read_b128 v[154:157], v154 offset:3072
	ds_read_b128 v[158:161], v170
	ds_read_b128 v[162:165], v170 offset:1024
	ds_read_b128 v[166:169], v170 offset:2048
	ds_read_b128 v[170:173], v170 offset:3072
	v_lshl_add_u64 v[214:215], s[70:71], 0, v[136:137]
	s_add_i32 m0, s50, 0xc000
	ds_read_b128 v[174:177], v141
	ds_read_b128 v[178:181], v141 offset:1024
	ds_read_b128 v[182:185], v141 offset:2048
	ds_read_b128 v[186:189], v141 offset:3072
	ds_read_b128 v[190:193], v141 offset:4096
	ds_read_b128 v[194:197], v141 offset:5120
	ds_read_b128 v[198:201], v141 offset:6144
	ds_read_b128 v[202:205], v141 offset:7168
	global_load_lds_dwordx4 v[214:215], off
	v_lshl_add_u64 v[214:215], s[70:71], 0, v[138:139]
	s_add_i32 m0, s50, 0xe000
	s_nop 0
	s_nop 0
	global_load_lds_dwordx4 v[214:215], off
	s_waitcnt vmcnt(8)
	s_waitcnt lgkmcnt(0)
	s_barrier
	s_setprio 1
	v_mfma_f32_16x16x32_bf16 v[126:129], v[142:145], v[174:177], v[126:129]
	v_mfma_f32_16x16x32_bf16 v[126:129], v[146:149], v[178:181], v[126:129]
	v_mfma_f32_16x16x32_bf16 v[122:125], v[150:153], v[174:177], v[122:125]
	v_mfma_f32_16x16x32_bf16 v[122:125], v[154:157], v[178:181], v[122:125]
	v_mfma_f32_16x16x32_bf16 v[106:109], v[150:153], v[182:185], v[106:109]
	v_mfma_f32_16x16x32_bf16 v[106:109], v[154:157], v[186:189], v[106:109]
	v_mfma_f32_16x16x32_bf16 v[110:113], v[142:145], v[182:185], v[110:113]
	v_mfma_f32_16x16x32_bf16 v[110:113], v[146:149], v[186:189], v[110:113]
	v_mfma_f32_16x16x32_bf16 v[94:97], v[142:145], v[190:193], v[94:97]
	v_mfma_f32_16x16x32_bf16 v[94:97], v[146:149], v[194:197], v[94:97]
	v_mfma_f32_16x16x32_bf16 v[90:93], v[150:153], v[190:193], v[90:93]
	v_mfma_f32_16x16x32_bf16 v[90:93], v[154:157], v[194:197], v[90:93]
	v_mfma_f32_16x16x32_bf16 v[74:77], v[150:153], v[198:201], v[74:77]
	v_mfma_f32_16x16x32_bf16 v[74:77], v[154:157], v[202:205], v[74:77]
	v_mfma_f32_16x16x32_bf16 v[78:81], v[142:145], v[198:201], v[78:81]
	v_mfma_f32_16x16x32_bf16 v[78:81], v[146:149], v[202:205], v[78:81]
	v_mfma_f32_16x16x32_bf16 v[118:121], v[158:161], v[174:177], v[118:121]
	v_mfma_f32_16x16x32_bf16 v[118:121], v[162:165], v[178:181], v[118:121]
	v_mfma_f32_16x16x32_bf16 v[114:117], v[166:169], v[174:177], v[114:117]
	v_mfma_f32_16x16x32_bf16 v[114:117], v[170:173], v[178:181], v[114:117]
	v_mfma_f32_16x16x32_bf16 v[98:101], v[166:169], v[182:185], v[98:101]
	v_mfma_f32_16x16x32_bf16 v[98:101], v[170:173], v[186:189], v[98:101]
	v_mfma_f32_16x16x32_bf16 v[102:105], v[158:161], v[182:185], v[102:105]
	v_mfma_f32_16x16x32_bf16 v[102:105], v[162:165], v[186:189], v[102:105]
	v_mfma_f32_16x16x32_bf16 v[86:89], v[158:161], v[190:193], v[86:89]
	v_mfma_f32_16x16x32_bf16 v[86:89], v[162:165], v[194:197], v[86:89]
	v_mfma_f32_16x16x32_bf16 v[82:85], v[166:169], v[190:193], v[82:85]
	v_mfma_f32_16x16x32_bf16 v[82:85], v[170:173], v[194:197], v[82:85]
	s_setprio 2
	s_barrier
	v_mfma_f32_16x16x32_bf16 v[66:69], v[166:169], v[198:201], v[66:69]
	v_mfma_f32_16x16x32_bf16 v[66:69], v[170:173], v[202:205], v[66:69]
	v_mfma_f32_16x16x32_bf16 v[70:73], v[158:161], v[198:201], v[70:73]
	v_mfma_f32_16x16x32_bf16 v[70:73], v[162:165], v[202:205], v[70:73]
	s_setprio 0
	s_nop 0
	s_add_i32 s60, s61, s39
	s_nop 0
	v_lshl_add_u64 v[214:215], s[4:5], 0, v[130:131]
	s_mov_b32 m0, s60
	s_nop 0
	ds_read_b128 v[174:177], v141 offset:16384
	ds_read_b128 v[178:181], v141 offset:17408
	ds_read_b128 v[182:185], v141 offset:18432
	ds_read_b128 v[186:189], v141 offset:19456
	ds_read_b128 v[190:193], v141 offset:20480
	ds_read_b128 v[194:197], v141 offset:21504
	ds_read_b128 v[198:201], v141 offset:22528
	ds_read_b128 v[202:205], v141 offset:23552
	global_load_lds_dwordx4 v[214:215], off
	s_add_i32 m0, s60, 0x2000
	s_add_u32 s60, s4, 0xb0000
	v_lshl_add_u64 v[216:217], s[4:5], 0, v[134:135]
	s_addc_u32 s61, s5, 0
	s_add_i32 s59, s59, s39
	global_load_lds_dwordx4 v[216:217], off
	v_lshl_add_u64 v[218:219], s[60:61], 0, v[130:131]
	s_mov_b32 m0, s59
	s_nop 0
	v_lshl_add_u64 v[220:221], s[30:31], 0, v[134:135]
	global_load_lds_dwordx4 v[218:219], off
	v_lshl_add_u64 v[218:219], s[60:61], 0, v[134:135]
	s_add_i32 m0, s59, 0x2000
	s_nop 0
	s_nop 0
	global_load_lds_dwordx4 v[218:219], off
	v_lshl_add_u64 v[218:219], s[30:31], 0, v[130:131]
	s_mov_b32 m0, s50
	s_nop 0
	global_load_lds_dwordx4 v[218:219], off
	s_mov_b32 m0, s51
	s_nop 0
	global_load_lds_dwordx4 v[220:221], off
	s_waitcnt vmcnt(8)
	s_waitcnt lgkmcnt(0)
	s_barrier
	s_setprio 1
	v_mfma_f32_16x16x32_bf16 v[62:65], v[142:145], v[174:177], v[62:65]
	v_mfma_f32_16x16x32_bf16 v[62:65], v[146:149], v[178:181], v[62:65]
	v_mfma_f32_16x16x32_bf16 v[58:61], v[150:153], v[174:177], v[58:61]
	v_mfma_f32_16x16x32_bf16 v[58:61], v[154:157], v[178:181], v[58:61]
	v_mfma_f32_16x16x32_bf16 v[42:45], v[150:153], v[182:185], v[42:45]
	v_mfma_f32_16x16x32_bf16 v[42:45], v[154:157], v[186:189], v[42:45]
	v_mfma_f32_16x16x32_bf16 v[46:49], v[142:145], v[182:185], v[46:49]
	v_mfma_f32_16x16x32_bf16 v[46:49], v[146:149], v[186:189], v[46:49]
	v_mfma_f32_16x16x32_bf16 v[30:33], v[142:145], v[190:193], v[30:33]
	v_mfma_f32_16x16x32_bf16 v[30:33], v[146:149], v[194:197], v[30:33]
	v_mfma_f32_16x16x32_bf16 v[26:29], v[150:153], v[190:193], v[26:29]
	v_mfma_f32_16x16x32_bf16 v[26:29], v[154:157], v[194:197], v[26:29]
	v_mfma_f32_16x16x32_bf16 v[10:13], v[150:153], v[198:201], v[10:13]
	v_mfma_f32_16x16x32_bf16 v[10:13], v[154:157], v[202:205], v[10:13]
	v_mfma_f32_16x16x32_bf16 v[14:17], v[142:145], v[198:201], v[14:17]
	v_mfma_f32_16x16x32_bf16 v[14:17], v[146:149], v[202:205], v[14:17]
	v_mfma_f32_16x16x32_bf16 v[54:57], v[158:161], v[174:177], v[54:57]
	v_mfma_f32_16x16x32_bf16 v[54:57], v[162:165], v[178:181], v[54:57]
	v_mfma_f32_16x16x32_bf16 v[50:53], v[166:169], v[174:177], v[50:53]
	v_mfma_f32_16x16x32_bf16 v[50:53], v[170:173], v[178:181], v[50:53]
	v_mfma_f32_16x16x32_bf16 v[34:37], v[166:169], v[182:185], v[34:37]
	v_mfma_f32_16x16x32_bf16 v[34:37], v[170:173], v[186:189], v[34:37]
	v_mfma_f32_16x16x32_bf16 v[38:41], v[158:161], v[182:185], v[38:41]
	v_mfma_f32_16x16x32_bf16 v[38:41], v[162:165], v[186:189], v[38:41]
	v_mfma_f32_16x16x32_bf16 v[22:25], v[158:161], v[190:193], v[22:25]
	v_mfma_f32_16x16x32_bf16 v[22:25], v[162:165], v[194:197], v[22:25]
	v_mfma_f32_16x16x32_bf16 v[18:21], v[166:169], v[190:193], v[18:21]
	v_mfma_f32_16x16x32_bf16 v[18:21], v[170:173], v[194:197], v[18:21]
	s_setprio 2
	s_barrier
	v_mfma_f32_16x16x32_bf16 v[2:5], v[166:169], v[198:201], v[2:5]
	v_mfma_f32_16x16x32_bf16 v[2:5], v[170:173], v[202:205], v[2:5]
	v_mfma_f32_16x16x32_bf16 v[6:9], v[158:161], v[198:201], v[6:9]
	v_mfma_f32_16x16x32_bf16 v[6:9], v[162:165], v[202:205], v[6:9]
	s_setprio 0
	s_nop 0
	s_add_i32 s59, 0, 0x18000
	s_add_i32 s60, 0, 0x1c000
	v_add_u32_e32 v154, s59, v140
	v_add_u32_e32 v170, s60, v140
	ds_read_b128 v[142:145], v154
	ds_read_b128 v[146:149], v154 offset:1024
	ds_read_b128 v[150:153], v154 offset:2048
	ds_read_b128 v[154:157], v154 offset:3072
	ds_read_b128 v[158:161], v170
	ds_read_b128 v[162:165], v170 offset:1024
	ds_read_b128 v[166:169], v170 offset:2048
	ds_read_b128 v[170:173], v170 offset:3072
	s_add_u32 s30, s30, 0xb0000
	s_addc_u32 s31, s31, 0
	s_mov_b32 m0, s52
	v_lshl_add_u64 v[222:223], s[30:31], 0, v[130:131]
	ds_read_b128 v[174:177], v141 offset:32768
	ds_read_b128 v[178:181], v141 offset:33792
	ds_read_b128 v[182:185], v141 offset:34816
	ds_read_b128 v[186:189], v141 offset:35840
	ds_read_b128 v[190:193], v141 offset:36864
	ds_read_b128 v[194:197], v141 offset:37888
	ds_read_b128 v[198:201], v141 offset:38912
	ds_read_b128 v[202:205], v141 offset:39936
	global_load_lds_dwordx4 v[222:223], off
	v_lshl_add_u64 v[222:223], s[30:31], 0, v[134:135]
	s_mov_b32 m0, s53
	s_nop 0
	global_load_lds_dwordx4 v[222:223], off
	s_waitcnt vmcnt(8)
	s_waitcnt lgkmcnt(0)
	s_barrier
	s_setprio 1
	v_mfma_f32_16x16x32_bf16 v[126:129], v[142:145], v[174:177], v[126:129]
	v_mfma_f32_16x16x32_bf16 v[126:129], v[146:149], v[178:181], v[126:129]
	v_mfma_f32_16x16x32_bf16 v[122:125], v[150:153], v[174:177], v[122:125]
	v_mfma_f32_16x16x32_bf16 v[122:125], v[154:157], v[178:181], v[122:125]
	v_mfma_f32_16x16x32_bf16 v[106:109], v[150:153], v[182:185], v[106:109]
	v_mfma_f32_16x16x32_bf16 v[106:109], v[154:157], v[186:189], v[106:109]
	v_mfma_f32_16x16x32_bf16 v[110:113], v[142:145], v[182:185], v[110:113]
	v_mfma_f32_16x16x32_bf16 v[110:113], v[146:149], v[186:189], v[110:113]
	v_mfma_f32_16x16x32_bf16 v[94:97], v[142:145], v[190:193], v[94:97]
	v_mfma_f32_16x16x32_bf16 v[94:97], v[146:149], v[194:197], v[94:97]
	v_mfma_f32_16x16x32_bf16 v[90:93], v[150:153], v[190:193], v[90:93]
	v_mfma_f32_16x16x32_bf16 v[90:93], v[154:157], v[194:197], v[90:93]
	v_mfma_f32_16x16x32_bf16 v[74:77], v[150:153], v[198:201], v[74:77]
	v_mfma_f32_16x16x32_bf16 v[74:77], v[154:157], v[202:205], v[74:77]
	v_mfma_f32_16x16x32_bf16 v[78:81], v[142:145], v[198:201], v[78:81]
	v_mfma_f32_16x16x32_bf16 v[78:81], v[146:149], v[202:205], v[78:81]
	v_mfma_f32_16x16x32_bf16 v[118:121], v[158:161], v[174:177], v[118:121]
	v_mfma_f32_16x16x32_bf16 v[118:121], v[162:165], v[178:181], v[118:121]
	v_mfma_f32_16x16x32_bf16 v[114:117], v[166:169], v[174:177], v[114:117]
	v_mfma_f32_16x16x32_bf16 v[114:117], v[170:173], v[178:181], v[114:117]
	v_mfma_f32_16x16x32_bf16 v[98:101], v[166:169], v[182:185], v[98:101]
	v_mfma_f32_16x16x32_bf16 v[98:101], v[170:173], v[186:189], v[98:101]
	v_mfma_f32_16x16x32_bf16 v[102:105], v[158:161], v[182:185], v[102:105]
	v_mfma_f32_16x16x32_bf16 v[102:105], v[162:165], v[186:189], v[102:105]
	v_mfma_f32_16x16x32_bf16 v[86:89], v[158:161], v[190:193], v[86:89]
	v_mfma_f32_16x16x32_bf16 v[86:89], v[162:165], v[194:197], v[86:89]
	v_mfma_f32_16x16x32_bf16 v[82:85], v[166:169], v[190:193], v[82:85]
	v_mfma_f32_16x16x32_bf16 v[82:85], v[170:173], v[194:197], v[82:85]
	s_setprio 2
	s_barrier
	v_mfma_f32_16x16x32_bf16 v[66:69], v[166:169], v[198:201], v[66:69]
	v_mfma_f32_16x16x32_bf16 v[66:69], v[170:173], v[202:205], v[66:69]
	v_mfma_f32_16x16x32_bf16 v[70:73], v[158:161], v[198:201], v[70:73]
	v_mfma_f32_16x16x32_bf16 v[70:73], v[162:165], v[202:205], v[70:73]
	s_setprio 0
	s_nop 0
	s_add_i32 s30, s59, s39
	s_nop 0
	v_lshl_add_u64 v[214:215], v[214:215], 0, s[24:25]
	s_mov_b32 m0, s30
	s_nop 0
	ds_read_b128 v[174:177], v141 offset:49152
	ds_read_b128 v[178:181], v141 offset:50176
	ds_read_b128 v[182:185], v141 offset:51200
	ds_read_b128 v[186:189], v141 offset:52224
	ds_read_b128 v[190:193], v141 offset:53248
	ds_read_b128 v[194:197], v141 offset:54272
	ds_read_b128 v[198:201], v141 offset:55296
	ds_read_b128 v[202:205], v141 offset:56320
	global_load_lds_dwordx4 v[214:215], off
	s_add_i32 m0, s30, 0x2000
	s_add_u32 s4, s4, 0xb0080
	v_lshl_add_u64 v[214:215], v[216:217], 0, s[24:25]
	s_addc_u32 s5, s5, 0
	s_add_i32 s30, s60, s39
	global_load_lds_dwordx4 v[214:215], off
	v_lshl_add_u64 v[214:215], s[4:5], 0, v[130:131]
	s_mov_b32 m0, s30
	s_nop 0
	global_load_lds_dwordx4 v[214:215], off
	v_lshl_add_u64 v[214:215], s[4:5], 0, v[134:135]
	s_add_i32 m0, s30, 0x2000
	s_nop 0
	s_nop 0
	global_load_lds_dwordx4 v[214:215], off
	v_lshl_add_u64 v[214:215], v[218:219], 0, s[24:25]
	s_mov_b32 m0, s54
	s_nop 0
	global_load_lds_dwordx4 v[214:215], off
	v_lshl_add_u64 v[214:215], v[220:221], 0, s[24:25]
	s_mov_b32 m0, s55
	s_nop 0
	global_load_lds_dwordx4 v[214:215], off
	s_waitcnt vmcnt(8)
	s_waitcnt lgkmcnt(0)
	s_barrier
	s_setprio 1
	v_mfma_f32_16x16x32_bf16 v[62:65], v[142:145], v[174:177], v[62:65]
	v_mfma_f32_16x16x32_bf16 v[62:65], v[146:149], v[178:181], v[62:65]
	v_mfma_f32_16x16x32_bf16 v[58:61], v[150:153], v[174:177], v[58:61]
	v_mfma_f32_16x16x32_bf16 v[58:61], v[154:157], v[178:181], v[58:61]
	v_mfma_f32_16x16x32_bf16 v[42:45], v[150:153], v[182:185], v[42:45]
	v_mfma_f32_16x16x32_bf16 v[42:45], v[154:157], v[186:189], v[42:45]
	v_mfma_f32_16x16x32_bf16 v[46:49], v[142:145], v[182:185], v[46:49]
	v_mfma_f32_16x16x32_bf16 v[46:49], v[146:149], v[186:189], v[46:49]
	v_mfma_f32_16x16x32_bf16 v[30:33], v[142:145], v[190:193], v[30:33]
	v_mfma_f32_16x16x32_bf16 v[30:33], v[146:149], v[194:197], v[30:33]
	v_mfma_f32_16x16x32_bf16 v[26:29], v[150:153], v[190:193], v[26:29]
	v_mfma_f32_16x16x32_bf16 v[26:29], v[154:157], v[194:197], v[26:29]
	v_mfma_f32_16x16x32_bf16 v[10:13], v[150:153], v[198:201], v[10:13]
	v_mfma_f32_16x16x32_bf16 v[10:13], v[154:157], v[202:205], v[10:13]
	v_mfma_f32_16x16x32_bf16 v[14:17], v[142:145], v[198:201], v[14:17]
	v_mfma_f32_16x16x32_bf16 v[14:17], v[146:149], v[202:205], v[14:17]
	v_mfma_f32_16x16x32_bf16 v[54:57], v[158:161], v[174:177], v[54:57]
	v_mfma_f32_16x16x32_bf16 v[54:57], v[162:165], v[178:181], v[54:57]
	v_mfma_f32_16x16x32_bf16 v[50:53], v[166:169], v[174:177], v[50:53]
	v_mfma_f32_16x16x32_bf16 v[50:53], v[170:173], v[178:181], v[50:53]
	v_mfma_f32_16x16x32_bf16 v[34:37], v[166:169], v[182:185], v[34:37]
	v_mfma_f32_16x16x32_bf16 v[34:37], v[170:173], v[186:189], v[34:37]
	v_mfma_f32_16x16x32_bf16 v[38:41], v[158:161], v[182:185], v[38:41]
	v_mfma_f32_16x16x32_bf16 v[38:41], v[162:165], v[186:189], v[38:41]
	v_mfma_f32_16x16x32_bf16 v[22:25], v[158:161], v[190:193], v[22:25]
	v_mfma_f32_16x16x32_bf16 v[22:25], v[162:165], v[194:197], v[22:25]
	v_mfma_f32_16x16x32_bf16 v[18:21], v[166:169], v[190:193], v[18:21]
	v_mfma_f32_16x16x32_bf16 v[18:21], v[170:173], v[194:197], v[18:21]
	s_setprio 2
	s_barrier
	v_mfma_f32_16x16x32_bf16 v[2:5], v[166:169], v[198:201], v[2:5]
	v_mfma_f32_16x16x32_bf16 v[2:5], v[170:173], v[202:205], v[2:5]
	v_mfma_f32_16x16x32_bf16 v[6:9], v[158:161], v[198:201], v[6:9]
	v_mfma_f32_16x16x32_bf16 v[6:9], v[162:165], v[202:205], v[6:9]
	s_setprio 0
	s_nop 0
	s_add_i32 s58, s58, 2
	s_nop 0
	s_add_u32 s56, s56, 0x100
	s_addc_u32 s57, s57, 0
	s_nop 0
	s_add_u32 s2, s2, 0x100
	s_addc_u32 s3, s3, 0
	s_nop 0
	v_lshl_add_u64 v[136:137], v[136:137], 0, s[28:29]
	s_cmp_lt_u32 s58, 42
	s_nop 0
	v_lshl_add_u64 v[138:139], v[138:139], 0, s[28:29]
	s_cbranch_scc1 .LBB0_1018
	s_waitcnt vmcnt(0)
	s_cmpk_gt_u32 s36, 0xff
	s_cbranch_scc1 .LBB0_1021
	s_barrier
